# GEMM loops: k-inner MFMA order (same accumulator back-to-back, k0 then k1) with boustrophedon over (n,m); power probe
# speedup vs baseline: 1.0267x; 1.0194x over previous
; #define PG8_STAGE(bufoff, gbase, voff) do { _Pragma("unroll") for (int _i = 0; _i < 2; ++_i) \
;         __builtin_amdgcn_global_load_lds((const unsigned*)((const char*)(gbase) + (voff)[_i]), (LAS unsigned*)(lds + (bufoff) + ldsw + _i * 8192), 16, 0, 0); } while (0)
; #define PG8_LDA(dst, b, h) do { _Pragma("unroll") for (int m = 0; m < 4; ++m) _Pragma("unroll") for (int k = 0; k < 2; ++k) dst[m][k] = *(const LAS bf16x8*)(lds + PG8_SA(b, h) + aoff + m * 2048 + k * 1024); } while (0)
; #define PG8_LDB(dst, b, h) do { _Pragma("unroll") for (int n = 0; n < 2; ++n) _Pragma("unroll") for (int k = 0; k < 2; ++k) dst[n][k] = *(const LAS bf16x8*)(lds + PG8_SB(b, h) + boff + n * 2048 + k * 1024); } while (0)
; #define PG8_MMA(ai, bj, At, Bt) do { __builtin_amdgcn_s_setprio(1); _Pragma("unroll") for (int m = 0; m < 4; ++m) _Pragma("unroll") for (int n = 0; n < 2; ++n) _Pragma("unroll") for (int k = 0; k < 2; ++k) \
;         acc[ai][bj][m][n] = __builtin_amdgcn_mfma_f32_16x16x32_bf16(Bt[n][k], At[m][k], acc[ai][bj][m][n], 0, 0, 0); __builtin_amdgcn_s_setprio(0); } while (0)
; #define PG8_WAIT_V(n) asm volatile("s_waitcnt vmcnt(" #n ")" ::: "memory")
; #define PG8_WAIT_L(n) asm volatile("s_waitcnt lgkmcnt(" #n ")" ::: "memory")
; template <class Epi, class Sched, bool ALIGN_EPI = false, bool SP2 = false>
; __device__ __forceinline__ void gemm_phase(LAS unsigned char* lds, const Gemm g, const Sched& S, const Epi& E) {
;     ...
;         for (int t = 0; t < nt; t += 2) {
;             const bool last = (t == nt - 2);
;             const char* a1 = cA + (size_t)(t + 1) * kstep;
;             const char* a2 = last ? nA : cA + (size_t)(t + 2) * kstep; const char* b2 = last ? nB : cB + (size_t)(t + 2) * kstep;
;             const char* a3 = a2 + kstep; const char* b3 = b2 + kstep;
;             if (last && has_next) S.a_ready(nxt);
;             if constexpr (SP2) {
;             PG8_LDB(B0, 0, 0); PG8_LDB(B1, 0, 1); PG8_SCHED; PG8_LDA(At, 0, 0); PG8_STAGE(PG8_SA(1, 1), a1 + hstep, voffA);
;             PG8_WAIT_V(8); PG8_WAIT_L(0); PG8_BAR; PG8_MMA(0, 0, At, B0); PG8_MMA(0, 1, At, B1); PG8_BAR; PG8_SCHED;
;             PG8_LDA(At, 0, 1); PG8_STAGE(PG8_SB(0, 0), b2, voffB); PG8_STAGE(PG8_SB(0, 1), b2 + hstep, voffB); PG8_STAGE(PG8_SA(0, 0), a2, voffA);
;             PG8_WAIT_V(8); PG8_WAIT_L(0); PG8_BAR; PG8_MMA(1, 0, At, B0); PG8_MMA(1, 1, At, B1); PG8_BAR; PG8_SCHED;
.LBB0_173:
	s_add_u32 s26, s24, 0xfff80080
	s_addc_u32 s27, s25, -1
	s_add_i32 s45, 0, 0x10000
	s_cmp_eq_u32 s44, 28
	s_cselect_b32 s29, s7, s27
	s_cselect_b32 s28, s8, s26
	v_add_u32_e32 v140, s45, v145
	s_cselect_b32 s27, s17, s43
	s_cselect_b32 s26, s19, s35
	s_add_i32 s47, 0, 0x14000
	ds_read_b128 v[150:153], v140
	ds_read_b128 v[154:157], v140 offset:1024
	ds_read_b128 v[158:161], v140 offset:2048
	ds_read_b128 v[162:165], v140 offset:3072
	v_add_u32_e32 v140, s47, v145
	ds_read_b128 v[166:169], v140
	ds_read_b128 v[170:173], v140 offset:1024
	ds_read_b128 v[174:177], v140 offset:2048
	ds_read_b128 v[178:181], v140 offset:3072
	v_lshl_add_u64 v[140:141], s[24:25], 0, v[136:137]
	s_add_i32 m0, s30, 0xc000
	ds_read_b128 v[182:185], v149
	ds_read_b128 v[194:197], v149 offset:1024
	ds_read_b128 v[198:201], v149 offset:2048
	ds_read_b128 v[202:205], v149 offset:3072
	ds_read_b128 v[206:209], v149 offset:4096
	ds_read_b128 v[210:213], v149 offset:5120
	ds_read_b128 v[214:217], v149 offset:6144
	ds_read_b128 v[218:221], v149 offset:7168
	global_load_lds_dwordx4 v[140:141], off
	v_lshl_add_u64 v[140:141], s[24:25], 0, v[138:139]
	s_add_i32 m0, s30, 0xe000
	s_nop 0
	global_load_lds_dwordx4 v[140:141], off
	s_waitcnt vmcnt(8)
	s_waitcnt lgkmcnt(0)
	s_barrier
	s_setprio 1
	s_waitcnt lgkmcnt(0)
	v_mfma_f32_16x16x32_bf16 v[126:129], v[150:153], v[182:185], v[126:129]
	v_mfma_f32_16x16x32_bf16 v[126:129], v[154:157], v[194:197], v[126:129]
	v_mfma_f32_16x16x32_bf16 v[122:125], v[158:161], v[182:185], v[122:125]
	v_mfma_f32_16x16x32_bf16 v[122:125], v[162:165], v[194:197], v[122:125]
	v_mfma_f32_16x16x32_bf16 v[106:109], v[158:161], v[198:201], v[106:109]
	v_mfma_f32_16x16x32_bf16 v[106:109], v[162:165], v[202:205], v[106:109]
	v_mfma_f32_16x16x32_bf16 v[110:113], v[150:153], v[198:201], v[110:113]
	v_mfma_f32_16x16x32_bf16 v[110:113], v[154:157], v[202:205], v[110:113]
	v_mfma_f32_16x16x32_bf16 v[94:97], v[150:153], v[206:209], v[94:97]
	v_mfma_f32_16x16x32_bf16 v[94:97], v[154:157], v[210:213], v[94:97]
	v_mfma_f32_16x16x32_bf16 v[90:93], v[158:161], v[206:209], v[90:93]
	v_mfma_f32_16x16x32_bf16 v[90:93], v[162:165], v[210:213], v[90:93]
	v_mfma_f32_16x16x32_bf16 v[74:77], v[158:161], v[214:217], v[74:77]
	v_mfma_f32_16x16x32_bf16 v[74:77], v[162:165], v[218:221], v[74:77]
	v_mfma_f32_16x16x32_bf16 v[78:81], v[150:153], v[214:217], v[78:81]
	v_mfma_f32_16x16x32_bf16 v[78:81], v[154:157], v[218:221], v[78:81]
	s_setprio 0
	s_setprio 1
	v_mfma_f32_16x16x32_bf16 v[118:121], v[166:169], v[182:185], v[118:121]
	v_mfma_f32_16x16x32_bf16 v[118:121], v[170:173], v[194:197], v[118:121]
	v_mfma_f32_16x16x32_bf16 v[114:117], v[174:177], v[182:185], v[114:117]
	v_mfma_f32_16x16x32_bf16 v[114:117], v[178:181], v[194:197], v[114:117]
	v_mfma_f32_16x16x32_bf16 v[98:101], v[174:177], v[198:201], v[98:101]
	v_mfma_f32_16x16x32_bf16 v[98:101], v[178:181], v[202:205], v[98:101]
	v_mfma_f32_16x16x32_bf16 v[102:105], v[166:169], v[198:201], v[102:105]
	v_mfma_f32_16x16x32_bf16 v[102:105], v[170:173], v[202:205], v[102:105]
	v_mfma_f32_16x16x32_bf16 v[86:89], v[166:169], v[206:209], v[86:89]
	v_mfma_f32_16x16x32_bf16 v[86:89], v[170:173], v[210:213], v[86:89]
	v_mfma_f32_16x16x32_bf16 v[82:85], v[174:177], v[206:209], v[82:85]
	v_mfma_f32_16x16x32_bf16 v[82:85], v[178:181], v[210:213], v[82:85]
	v_mfma_f32_16x16x32_bf16 v[66:69], v[174:177], v[214:217], v[66:69]
	v_mfma_f32_16x16x32_bf16 v[66:69], v[178:181], v[218:221], v[66:69]
	v_mfma_f32_16x16x32_bf16 v[70:73], v[166:169], v[214:217], v[70:73]
	v_mfma_f32_16x16x32_bf16 v[70:73], v[170:173], v[218:221], v[70:73]
	s_setprio 0
	s_barrier
	s_add_i32 s45, s45, s9
	v_lshl_add_u64 v[140:141], s[26:27], 0, v[0:1]
	s_mov_b32 m0, s45
	ds_read_b128 v[182:185], v149 offset:16384
	ds_read_b128 v[194:197], v149 offset:17408
	ds_read_b128 v[198:201], v149 offset:18432
	ds_read_b128 v[202:205], v149 offset:19456
	ds_read_b128 v[206:209], v149 offset:20480
	ds_read_b128 v[210:213], v149 offset:21504
	ds_read_b128 v[214:217], v149 offset:22528
	ds_read_b128 v[218:221], v149 offset:23552
	global_load_lds_dwordx4 v[140:141], off
	s_add_i32 m0, s45, 0x2000
	s_add_u32 s48, s26, 0x80000
	v_lshl_add_u64 v[186:187], s[26:27], 0, v[130:131]
	s_addc_u32 s49, s27, 0
	s_add_i32 s45, s47, s9
	global_load_lds_dwordx4 v[186:187], off
	v_lshl_add_u64 v[188:189], s[48:49], 0, v[0:1]
	s_mov_b32 m0, s45
	v_lshl_add_u64 v[190:191], s[28:29], 0, v[132:133]
	global_load_lds_dwordx4 v[188:189], off
	v_lshl_add_u64 v[188:189], s[48:49], 0, v[130:131]
	s_add_i32 m0, s45, 0x2000
	s_nop 0
	global_load_lds_dwordx4 v[188:189], off
	v_lshl_add_u64 v[188:189], s[28:29], 0, v[134:135]
	s_mov_b32 m0, s30
	s_nop 0
	global_load_lds_dwordx4 v[188:189], off
	s_mov_b32 m0, s31
	s_nop 0
	global_load_lds_dwordx4 v[190:191], off
	s_waitcnt vmcnt(8)
	s_waitcnt lgkmcnt(0)
	s_barrier
; #define PG8_STAGE(bufoff, gbase, voff) do { _Pragma("unroll") for (int _i = 0; _i < 2; ++_i) \
;         __builtin_amdgcn_global_load_lds((const unsigned*)((const char*)(gbase) + (voff)[_i]), (LAS unsigned*)(lds + (bufoff) + ldsw + _i * 8192), 16, 0, 0); } while (0)
; #define PG8_LDA(dst, b, h) do { _Pragma("unroll") for (int m = 0; m < 4; ++m) _Pragma("unroll") for (int k = 0; k < 2; ++k) dst[m][k] = *(const LAS bf16x8*)(lds + PG8_SA(b, h) + aoff + m * 2048 + k * 1024); } while (0)
; #define PG8_LDB(dst, b, h) do { _Pragma("unroll") for (int n = 0; n < 2; ++n) _Pragma("unroll") for (int k = 0; k < 2; ++k) dst[n][k] = *(const LAS bf16x8*)(lds + PG8_SB(b, h) + boff + n * 2048 + k * 1024); } while (0)
; #define PG8_MMA(ai, bj, At, Bt) do { __builtin_amdgcn_s_setprio(1); _Pragma("unroll") for (int m = 0; m < 4; ++m) _Pragma("unroll") for (int n = 0; n < 2; ++n) _Pragma("unroll") for (int k = 0; k < 2; ++k) \
;         acc[ai][bj][m][n] = __builtin_amdgcn_mfma_f32_16x16x32_bf16(Bt[n][k], At[m][k], acc[ai][bj][m][n], 0, 0, 0); __builtin_amdgcn_s_setprio(0); } while (0)
; #define PG8_WAIT_V(n) asm volatile("s_waitcnt vmcnt(" #n ")" ::: "memory")
; #define PG8_WAIT_L(n) asm volatile("s_waitcnt lgkmcnt(" #n ")" ::: "memory")
; #define PG8_BAR __builtin_amdgcn_s_barrier()
; #define PG8_SCHED __builtin_amdgcn_sched_barrier(0)
; template <class Epi, class Sched, bool ALIGN_EPI = false, bool SP2 = false>
; __device__ __forceinline__ void gemm_phase(LAS unsigned char* lds, const Gemm g, const Sched& S, const Epi& E) {
;     ...
;             PG8_WAIT_V(8); PG8_WAIT_L(0); PG8_BAR; PG8_MMA(1, 0, At, B0); PG8_MMA(1, 1, At, B1); PG8_BAR; PG8_SCHED;
;             PG8_LDB(B0, 1, 0); PG8_LDB(B1, 1, 1); PG8_SCHED; PG8_LDA(At, 1, 0); PG8_STAGE(PG8_SA(0, 1), a2 + hstep, voffA);
;             PG8_WAIT_V(8); PG8_WAIT_L(0); PG8_BAR; PG8_MMA(0, 0, At, B0); PG8_MMA(0, 1, At, B1); PG8_BAR; PG8_SCHED;
	s_setprio 1
	s_waitcnt lgkmcnt(0)
	v_mfma_f32_16x16x32_bf16 v[62:65], v[150:153], v[182:185], v[62:65]
	v_mfma_f32_16x16x32_bf16 v[62:65], v[154:157], v[194:197], v[62:65]
	v_mfma_f32_16x16x32_bf16 v[58:61], v[158:161], v[182:185], v[58:61]
	v_mfma_f32_16x16x32_bf16 v[58:61], v[162:165], v[194:197], v[58:61]
	v_mfma_f32_16x16x32_bf16 v[42:45], v[158:161], v[198:201], v[42:45]
	v_mfma_f32_16x16x32_bf16 v[42:45], v[162:165], v[202:205], v[42:45]
	v_mfma_f32_16x16x32_bf16 v[46:49], v[150:153], v[198:201], v[46:49]
	v_mfma_f32_16x16x32_bf16 v[46:49], v[154:157], v[202:205], v[46:49]
	v_mfma_f32_16x16x32_bf16 v[30:33], v[150:153], v[206:209], v[30:33]
	v_mfma_f32_16x16x32_bf16 v[30:33], v[154:157], v[210:213], v[30:33]
	v_mfma_f32_16x16x32_bf16 v[26:29], v[158:161], v[206:209], v[26:29]
	v_mfma_f32_16x16x32_bf16 v[26:29], v[162:165], v[210:213], v[26:29]
	v_mfma_f32_16x16x32_bf16 v[10:13], v[158:161], v[214:217], v[10:13]
	v_mfma_f32_16x16x32_bf16 v[10:13], v[162:165], v[218:221], v[10:13]
	v_mfma_f32_16x16x32_bf16 v[14:17], v[150:153], v[214:217], v[14:17]
	v_mfma_f32_16x16x32_bf16 v[14:17], v[154:157], v[218:221], v[14:17]
	s_setprio 0
	s_setprio 1
	v_mfma_f32_16x16x32_bf16 v[54:57], v[166:169], v[182:185], v[54:57]
	v_mfma_f32_16x16x32_bf16 v[54:57], v[170:173], v[194:197], v[54:57]
	v_mfma_f32_16x16x32_bf16 v[50:53], v[174:177], v[182:185], v[50:53]
	v_mfma_f32_16x16x32_bf16 v[50:53], v[178:181], v[194:197], v[50:53]
	v_mfma_f32_16x16x32_bf16 v[34:37], v[174:177], v[198:201], v[34:37]
	v_mfma_f32_16x16x32_bf16 v[34:37], v[178:181], v[202:205], v[34:37]
	v_mfma_f32_16x16x32_bf16 v[38:41], v[166:169], v[198:201], v[38:41]
	v_mfma_f32_16x16x32_bf16 v[38:41], v[170:173], v[202:205], v[38:41]
	v_mfma_f32_16x16x32_bf16 v[22:25], v[166:169], v[206:209], v[22:25]
	v_mfma_f32_16x16x32_bf16 v[22:25], v[170:173], v[210:213], v[22:25]
	v_mfma_f32_16x16x32_bf16 v[18:21], v[174:177], v[206:209], v[18:21]
	v_mfma_f32_16x16x32_bf16 v[18:21], v[178:181], v[210:213], v[18:21]
	v_mfma_f32_16x16x32_bf16 v[2:5], v[174:177], v[214:217], v[2:5]
	v_mfma_f32_16x16x32_bf16 v[2:5], v[178:181], v[218:221], v[2:5]
	v_mfma_f32_16x16x32_bf16 v[6:9], v[166:169], v[214:217], v[6:9]
	v_mfma_f32_16x16x32_bf16 v[6:9], v[170:173], v[218:221], v[6:9]
	s_setprio 0
	s_barrier
	s_add_i32 s45, 0, 0x18000
	v_add_u32_e32 v142, s45, v145
	s_add_i32 s47, 0, 0x1c000
	ds_read_b128 v[150:153], v142
	ds_read_b128 v[154:157], v142 offset:1024
	ds_read_b128 v[158:161], v142 offset:2048
	ds_read_b128 v[162:165], v142 offset:3072
	v_add_u32_e32 v142, s47, v145
	ds_read_b128 v[166:169], v142
	ds_read_b128 v[170:173], v142 offset:1024
	ds_read_b128 v[174:177], v142 offset:2048
	ds_read_b128 v[178:181], v142 offset:3072
	s_add_u32 s28, s28, 0x80000
	s_addc_u32 s29, s29, 0
	s_mov_b32 m0, s38
	v_lshl_add_u64 v[192:193], s[28:29], 0, v[134:135]
	ds_read_b128 v[182:185], v149 offset:32768
	ds_read_b128 v[194:197], v149 offset:33792
	ds_read_b128 v[198:201], v149 offset:34816
	ds_read_b128 v[202:205], v149 offset:35840
	ds_read_b128 v[206:209], v149 offset:36864
	ds_read_b128 v[210:213], v149 offset:37888
	ds_read_b128 v[214:217], v149 offset:38912
	ds_read_b128 v[218:221], v149 offset:39936
	global_load_lds_dwordx4 v[192:193], off
	v_lshl_add_u64 v[192:193], s[28:29], 0, v[132:133]
	s_mov_b32 m0, s39
	s_nop 0
	global_load_lds_dwordx4 v[192:193], off
	s_waitcnt vmcnt(8)
	s_waitcnt lgkmcnt(0)
	s_barrier
	s_setprio 1
	s_waitcnt lgkmcnt(0)
	v_mfma_f32_16x16x32_bf16 v[126:129], v[150:153], v[182:185], v[126:129]
	v_mfma_f32_16x16x32_bf16 v[126:129], v[154:157], v[194:197], v[126:129]
	v_mfma_f32_16x16x32_bf16 v[122:125], v[158:161], v[182:185], v[122:125]
	v_mfma_f32_16x16x32_bf16 v[122:125], v[162:165], v[194:197], v[122:125]
	v_mfma_f32_16x16x32_bf16 v[106:109], v[158:161], v[198:201], v[106:109]
	v_mfma_f32_16x16x32_bf16 v[106:109], v[162:165], v[202:205], v[106:109]
	v_mfma_f32_16x16x32_bf16 v[110:113], v[150:153], v[198:201], v[110:113]
	v_mfma_f32_16x16x32_bf16 v[110:113], v[154:157], v[202:205], v[110:113]
	v_mfma_f32_16x16x32_bf16 v[94:97], v[150:153], v[206:209], v[94:97]
	v_mfma_f32_16x16x32_bf16 v[94:97], v[154:157], v[210:213], v[94:97]
	v_mfma_f32_16x16x32_bf16 v[90:93], v[158:161], v[206:209], v[90:93]
	v_mfma_f32_16x16x32_bf16 v[90:93], v[162:165], v[210:213], v[90:93]
	v_mfma_f32_16x16x32_bf16 v[74:77], v[158:161], v[214:217], v[74:77]
	v_mfma_f32_16x16x32_bf16 v[74:77], v[162:165], v[218:221], v[74:77]
	v_mfma_f32_16x16x32_bf16 v[78:81], v[150:153], v[214:217], v[78:81]
	v_mfma_f32_16x16x32_bf16 v[78:81], v[154:157], v[218:221], v[78:81]
	s_setprio 0
	s_setprio 1
	v_mfma_f32_16x16x32_bf16 v[118:121], v[166:169], v[182:185], v[118:121]
	v_mfma_f32_16x16x32_bf16 v[118:121], v[170:173], v[194:197], v[118:121]
	v_mfma_f32_16x16x32_bf16 v[114:117], v[174:177], v[182:185], v[114:117]
	v_mfma_f32_16x16x32_bf16 v[114:117], v[178:181], v[194:197], v[114:117]
	v_mfma_f32_16x16x32_bf16 v[98:101], v[174:177], v[198:201], v[98:101]
	v_mfma_f32_16x16x32_bf16 v[98:101], v[178:181], v[202:205], v[98:101]
	v_mfma_f32_16x16x32_bf16 v[102:105], v[166:169], v[198:201], v[102:105]
	v_mfma_f32_16x16x32_bf16 v[102:105], v[170:173], v[202:205], v[102:105]
	v_mfma_f32_16x16x32_bf16 v[86:89], v[166:169], v[206:209], v[86:89]
	v_mfma_f32_16x16x32_bf16 v[86:89], v[170:173], v[210:213], v[86:89]
	v_mfma_f32_16x16x32_bf16 v[82:85], v[174:177], v[206:209], v[82:85]
	v_mfma_f32_16x16x32_bf16 v[82:85], v[178:181], v[210:213], v[82:85]
	v_mfma_f32_16x16x32_bf16 v[66:69], v[174:177], v[214:217], v[66:69]
	v_mfma_f32_16x16x32_bf16 v[66:69], v[178:181], v[218:221], v[66:69]
	v_mfma_f32_16x16x32_bf16 v[70:73], v[166:169], v[214:217], v[70:73]
	v_mfma_f32_16x16x32_bf16 v[70:73], v[170:173], v[218:221], v[70:73]
	s_setprio 0
	s_barrier
; #define PG8_STAGE(bufoff, gbase, voff) do { _Pragma("unroll") for (int _i = 0; _i < 2; ++_i) \
;         __builtin_amdgcn_global_load_lds((const unsigned*)((const char*)(gbase) + (voff)[_i]), (LAS unsigned*)(lds + (bufoff) + ldsw + _i * 8192), 16, 0, 0); } while (0)
; #define PG8_LDA(dst, b, h) do { _Pragma("unroll") for (int m = 0; m < 4; ++m) _Pragma("unroll") for (int k = 0; k < 2; ++k) dst[m][k] = *(const LAS bf16x8*)(lds + PG8_SA(b, h) + aoff + m * 2048 + k * 1024); } while (0)
; #define PG8_MMA(ai, bj, At, Bt) do { __builtin_amdgcn_s_setprio(1); _Pragma("unroll") for (int m = 0; m < 4; ++m) _Pragma("unroll") for (int n = 0; n < 2; ++n) _Pragma("unroll") for (int k = 0; k < 2; ++k) \
;         acc[ai][bj][m][n] = __builtin_amdgcn_mfma_f32_16x16x32_bf16(Bt[n][k], At[m][k], acc[ai][bj][m][n], 0, 0, 0); __builtin_amdgcn_s_setprio(0); } while (0)
; #define PG8_WAIT_V(n) asm volatile("s_waitcnt vmcnt(" #n ")" ::: "memory")
; #define PG8_WAIT_L(n) asm volatile("s_waitcnt lgkmcnt(" #n ")" ::: "memory")
; #define PG8_BAR __builtin_amdgcn_s_barrier()
; #define PG8_SCHED __builtin_amdgcn_sched_barrier(0)
; template <class Epi, class Sched, bool ALIGN_EPI = false, bool SP2 = false>
; __device__ __forceinline__ void gemm_phase(LAS unsigned char* lds, const Gemm g, const Sched& S, const Epi& E) {
;     ...
;             PG8_LDA(At, 1, 1); PG8_STAGE(PG8_SB(1, 0), b3, voffB); PG8_STAGE(PG8_SB(1, 1), b3 + hstep, voffB); PG8_STAGE(PG8_SA(1, 0), a3, voffA);
;             PG8_WAIT_V(8); PG8_WAIT_L(0); PG8_BAR; PG8_MMA(1, 0, At, B0); PG8_MMA(1, 1, At, B1); PG8_BAR; PG8_SCHED;
	s_add_i32 s28, s45, s9
	v_lshl_add_u64 v[140:141], v[140:141], 0, s[12:13]
	s_mov_b32 m0, s28
	ds_read_b128 v[182:185], v149 offset:49152
	ds_read_b128 v[194:197], v149 offset:50176
	ds_read_b128 v[198:201], v149 offset:51200
	ds_read_b128 v[202:205], v149 offset:52224
	ds_read_b128 v[206:209], v149 offset:53248
	ds_read_b128 v[210:213], v149 offset:54272
	ds_read_b128 v[214:217], v149 offset:55296
	ds_read_b128 v[218:221], v149 offset:56320
	global_load_lds_dwordx4 v[140:141], off
	s_add_i32 m0, s28, 0x2000
	s_add_u32 s26, s26, 0x80080
	v_lshl_add_u64 v[140:141], v[186:187], 0, s[12:13]
	s_addc_u32 s27, s27, 0
	s_add_i32 s28, s47, s9
	global_load_lds_dwordx4 v[140:141], off
	v_lshl_add_u64 v[140:141], s[26:27], 0, v[0:1]
	s_mov_b32 m0, s28
	s_nop 0
	global_load_lds_dwordx4 v[140:141], off
	v_lshl_add_u64 v[140:141], s[26:27], 0, v[130:131]
	s_add_i32 m0, s28, 0x2000
	s_nop 0
	global_load_lds_dwordx4 v[140:141], off
	v_lshl_add_u64 v[140:141], v[188:189], 0, s[12:13]
	s_mov_b32 m0, s40
	s_nop 0
	global_load_lds_dwordx4 v[140:141], off
	v_lshl_add_u64 v[140:141], v[190:191], 0, s[12:13]
	s_mov_b32 m0, s41
	s_nop 0
	global_load_lds_dwordx4 v[140:141], off
	s_waitcnt vmcnt(8)
	s_waitcnt lgkmcnt(0)
	s_barrier
	s_setprio 1
	s_waitcnt lgkmcnt(0)
	v_mfma_f32_16x16x32_bf16 v[62:65], v[150:153], v[182:185], v[62:65]
	v_mfma_f32_16x16x32_bf16 v[62:65], v[154:157], v[194:197], v[62:65]
	v_mfma_f32_16x16x32_bf16 v[58:61], v[158:161], v[182:185], v[58:61]
	v_mfma_f32_16x16x32_bf16 v[58:61], v[162:165], v[194:197], v[58:61]
	v_mfma_f32_16x16x32_bf16 v[42:45], v[158:161], v[198:201], v[42:45]
	v_mfma_f32_16x16x32_bf16 v[42:45], v[162:165], v[202:205], v[42:45]
	v_mfma_f32_16x16x32_bf16 v[46:49], v[150:153], v[198:201], v[46:49]
	v_mfma_f32_16x16x32_bf16 v[46:49], v[154:157], v[202:205], v[46:49]
	v_mfma_f32_16x16x32_bf16 v[30:33], v[150:153], v[206:209], v[30:33]
	v_mfma_f32_16x16x32_bf16 v[30:33], v[154:157], v[210:213], v[30:33]
	v_mfma_f32_16x16x32_bf16 v[26:29], v[158:161], v[206:209], v[26:29]
	v_mfma_f32_16x16x32_bf16 v[26:29], v[162:165], v[210:213], v[26:29]
	v_mfma_f32_16x16x32_bf16 v[10:13], v[158:161], v[214:217], v[10:13]
	v_mfma_f32_16x16x32_bf16 v[10:13], v[162:165], v[218:221], v[10:13]
	v_mfma_f32_16x16x32_bf16 v[14:17], v[150:153], v[214:217], v[14:17]
	v_mfma_f32_16x16x32_bf16 v[14:17], v[154:157], v[218:221], v[14:17]
	s_setprio 0
	s_setprio 1
	v_mfma_f32_16x16x32_bf16 v[54:57], v[166:169], v[182:185], v[54:57]
	v_mfma_f32_16x16x32_bf16 v[54:57], v[170:173], v[194:197], v[54:57]
	v_mfma_f32_16x16x32_bf16 v[50:53], v[174:177], v[182:185], v[50:53]
	v_mfma_f32_16x16x32_bf16 v[50:53], v[178:181], v[194:197], v[50:53]
	v_mfma_f32_16x16x32_bf16 v[34:37], v[174:177], v[198:201], v[34:37]
	v_mfma_f32_16x16x32_bf16 v[34:37], v[178:181], v[202:205], v[34:37]
	v_mfma_f32_16x16x32_bf16 v[38:41], v[166:169], v[198:201], v[38:41]
	v_mfma_f32_16x16x32_bf16 v[38:41], v[170:173], v[202:205], v[38:41]
	v_mfma_f32_16x16x32_bf16 v[22:25], v[166:169], v[206:209], v[22:25]
	v_mfma_f32_16x16x32_bf16 v[22:25], v[170:173], v[210:213], v[22:25]
	v_mfma_f32_16x16x32_bf16 v[18:21], v[174:177], v[206:209], v[18:21]
	v_mfma_f32_16x16x32_bf16 v[18:21], v[178:181], v[210:213], v[18:21]
	v_mfma_f32_16x16x32_bf16 v[2:5], v[174:177], v[214:217], v[2:5]
	v_mfma_f32_16x16x32_bf16 v[2:5], v[178:181], v[218:221], v[2:5]
	v_mfma_f32_16x16x32_bf16 v[6:9], v[166:169], v[214:217], v[6:9]
	v_mfma_f32_16x16x32_bf16 v[6:9], v[170:173], v[218:221], v[6:9]
	s_setprio 0
	s_barrier
	s_add_i32 s44, s44, 2
	s_add_u32 s24, s24, 0x100
	s_addc_u32 s25, s25, 0
	s_add_u32 s35, s35, 0x100
	s_addc_u32 s43, s43, 0
	s_cmp_gt_u32 s44, 29
	s_cbranch_scc0 .LBB0_173
	s_and_b64 vcc, exec, s[4:5]
	s_cbranch_vccz .LBB0_176
	s_barrier

; #define PG8_STAGE(bufoff, gbase, voff) do { _Pragma("unroll") for (int _i = 0; _i < 2; ++_i) \
;         __builtin_amdgcn_global_load_lds((const unsigned*)((const char*)(gbase) + (voff)[_i]), (LAS unsigned*)(lds + (bufoff) + ldsw + _i * 8192), 16, 0, 0); } while (0)
; #define PG8_LDA(dst, b, h) do { _Pragma("unroll") for (int m = 0; m < 4; ++m) _Pragma("unroll") for (int k = 0; k < 2; ++k) dst[m][k] = *(const LAS bf16x8*)(lds + PG8_SA(b, h) + aoff + m * 2048 + k * 1024); } while (0)
; #define PG8_LDB(dst, b, h) do { _Pragma("unroll") for (int n = 0; n < 2; ++n) _Pragma("unroll") for (int k = 0; k < 2; ++k) dst[n][k] = *(const LAS bf16x8*)(lds + PG8_SB(b, h) + boff + n * 2048 + k * 1024); } while (0)
; #define PG8_WAIT_V(n) asm volatile("s_waitcnt vmcnt(" #n ")" ::: "memory")
; #define PG8_WAIT_L(n) asm volatile("s_waitcnt lgkmcnt(" #n ")" ::: "memory")
; #define PG8_BAR __builtin_amdgcn_s_barrier()
; #define PG8_SCHED __builtin_amdgcn_sched_barrier(0)
; template <class Epi, class Sched, bool ALIGN_EPI = false, bool SP2 = false>
; __device__ __forceinline__ void gemm_phase(LAS unsigned char* lds, const Gemm g, const Sched& S, const Epi& E) {
;     ...
;         const bool has_next = S.next(ui + 1, nxt);
;         const char* nA = has_next ? (const char*)g.A + (size_t)nxt.pm * tstep : cA; const char* nB = has_next ? (const char*)g.Bt + (size_t)nxt.pn * tstep : cB;
;         for (int t = 0; t < nt; t += 2) {
;             const bool last = (t == nt - 2);
;             const char* a1 = cA + (size_t)(t + 1) * kstep;
;             const char* a2 = last ? nA : cA + (size_t)(t + 2) * kstep; const char* b2 = last ? nB : cB + (size_t)(t + 2) * kstep;
;             const char* a3 = a2 + kstep; const char* b3 = b2 + kstep;
;             if (last && has_next) S.a_ready(nxt);
;             if constexpr (SP2) {
;             PG8_LDB(B0, 0, 0); PG8_LDB(B1, 0, 1); PG8_SCHED; PG8_LDA(At, 0, 0); PG8_STAGE(PG8_SA(1, 1), a1 + hstep, voffA);
;             PG8_WAIT_V(8); PG8_WAIT_L(0); PG8_BAR; PG8_MMA(0, 0, At, B0); PG8_MMA(0, 1, At, B1); PG8_BAR; PG8_SCHED;
;             PG8_LDA(At, 0, 1); PG8_STAGE(PG8_SB(0, 0), b2, voffB); PG8_STAGE(PG8_SB(0, 1), b2 + hstep, voffB); PG8_STAGE(PG8_SA(0, 0), a2, voffA);
;             PG8_WAIT_V(8); PG8_WAIT_L(0); PG8_BAR; PG8_MMA(1, 0, At, B0); PG8_MMA(1, 1, At, B1); PG8_BAR; PG8_SCHED;
.LBB0_257:
	s_add_u32 s24, s22, 0x100
	s_addc_u32 s25, s23, 0
	s_add_i32 s50, 0, 0x10000
	s_cmpk_eq_i32 s49, 0x54
	s_cselect_b32 s29, s1, s25
	s_cselect_b32 s28, s0, s24
	s_cselect_b32 s27, s21, s48
	s_cselect_b32 s26, s20, s47
	s_add_i32 s51, 0, 0x14000
	v_add_u32_e32 v126, s50, v247
	v_add_u32_e32 v158, s51, v247
	ds_read_b128 v[90:93], v126
	ds_read_b128 v[102:105], v126 offset:1024
	ds_read_b128 v[114:117], v126 offset:2048
	ds_read_b128 v[126:129], v126 offset:3072
	ds_read_b128 v[138:141], v158
	ds_read_b128 v[142:145], v158 offset:1024
	ds_read_b128 v[154:157], v158 offset:2048
	ds_read_b128 v[158:161], v158 offset:3072
	v_lshl_add_u64 v[186:187], s[22:23], 0, v[200:201]
	s_add_i32 m0, s6, 0xc000
	ds_read_b128 v[162:165], v249
	ds_read_b128 v[166:169], v249 offset:1024
	ds_read_b128 v[170:173], v249 offset:2048
	ds_read_b128 v[174:177], v249 offset:3072
	ds_read_b128 v[178:181], v249 offset:4096
	ds_read_b128 v[182:185], v249 offset:5120
	ds_read_b128 v[204:207], v249 offset:6144
	ds_read_b128 v[208:211], v249 offset:7168
	global_load_lds_dwordx4 v[186:187], off
	v_lshl_add_u64 v[186:187], s[22:23], 0, v[202:203]
	s_add_i32 m0, s6, 0xe000
	s_nop 0
	global_load_lds_dwordx4 v[186:187], off
	s_waitcnt vmcnt(8)
	s_waitcnt lgkmcnt(0)
	s_barrier
	s_setprio 1
	s_waitcnt lgkmcnt(0)
	v_mfma_f32_16x16x32_bf16 v[150:153], v[90:93], v[162:165], v[150:153]
	v_mfma_f32_16x16x32_bf16 v[150:153], v[102:105], v[166:169], v[150:153]
	v_mfma_f32_16x16x32_bf16 v[146:149], v[114:117], v[162:165], v[146:149]
	v_mfma_f32_16x16x32_bf16 v[146:149], v[126:129], v[166:169], v[146:149]
	v_mfma_f32_16x16x32_bf16 v[118:121], v[114:117], v[170:173], v[118:121]
	v_mfma_f32_16x16x32_bf16 v[118:121], v[126:129], v[174:177], v[118:121]
	v_mfma_f32_16x16x32_bf16 v[122:125], v[90:93], v[170:173], v[122:125]
	v_mfma_f32_16x16x32_bf16 v[122:125], v[102:105], v[174:177], v[122:125]
	v_mfma_f32_16x16x32_bf16 v[98:101], v[90:93], v[178:181], v[98:101]
	v_mfma_f32_16x16x32_bf16 v[98:101], v[102:105], v[182:185], v[98:101]
	v_mfma_f32_16x16x32_bf16 v[94:97], v[114:117], v[178:181], v[94:97]
	v_mfma_f32_16x16x32_bf16 v[94:97], v[126:129], v[182:185], v[94:97]
	v_mfma_f32_16x16x32_bf16 v[74:77], v[114:117], v[204:207], v[74:77]
	v_mfma_f32_16x16x32_bf16 v[74:77], v[126:129], v[208:211], v[74:77]
	v_mfma_f32_16x16x32_bf16 v[78:81], v[90:93], v[204:207], v[78:81]
	v_mfma_f32_16x16x32_bf16 v[78:81], v[102:105], v[208:211], v[78:81]
	s_setprio 0
	s_setprio 1
	v_mfma_f32_16x16x32_bf16 v[134:137], v[138:141], v[162:165], v[134:137]
	v_mfma_f32_16x16x32_bf16 v[134:137], v[142:145], v[166:169], v[134:137]
	v_mfma_f32_16x16x32_bf16 v[130:133], v[154:157], v[162:165], v[130:133]
	v_mfma_f32_16x16x32_bf16 v[130:133], v[158:161], v[166:169], v[130:133]
	v_mfma_f32_16x16x32_bf16 v[106:109], v[154:157], v[170:173], v[106:109]
	v_mfma_f32_16x16x32_bf16 v[106:109], v[158:161], v[174:177], v[106:109]
	v_mfma_f32_16x16x32_bf16 v[110:113], v[138:141], v[170:173], v[110:113]
	v_mfma_f32_16x16x32_bf16 v[110:113], v[142:145], v[174:177], v[110:113]
	v_mfma_f32_16x16x32_bf16 v[86:89], v[138:141], v[178:181], v[86:89]
	v_mfma_f32_16x16x32_bf16 v[86:89], v[142:145], v[182:185], v[86:89]
	v_mfma_f32_16x16x32_bf16 v[82:85], v[154:157], v[178:181], v[82:85]
	v_mfma_f32_16x16x32_bf16 v[82:85], v[158:161], v[182:185], v[82:85]
	v_mfma_f32_16x16x32_bf16 v[66:69], v[154:157], v[204:207], v[66:69]
	v_mfma_f32_16x16x32_bf16 v[66:69], v[158:161], v[208:211], v[66:69]
	v_mfma_f32_16x16x32_bf16 v[70:73], v[138:141], v[204:207], v[70:73]
	v_mfma_f32_16x16x32_bf16 v[70:73], v[142:145], v[208:211], v[70:73]
	s_setprio 0
	s_barrier
	s_add_i32 s22, s50, s2
	v_lshl_add_u64 v[186:187], s[26:27], 0, v[0:1]
	s_mov_b32 m0, s22
	ds_read_b128 v[162:165], v249 offset:16384
	ds_read_b128 v[166:169], v249 offset:17408
	ds_read_b128 v[170:173], v249 offset:18432
	ds_read_b128 v[174:177], v249 offset:19456
	ds_read_b128 v[178:181], v249 offset:20480
	ds_read_b128 v[182:185], v249 offset:21504
	ds_read_b128 v[204:207], v249 offset:22528
	ds_read_b128 v[208:211], v249 offset:23552
	global_load_lds_dwordx4 v[186:187], off
	s_add_i32 m0, s22, 0x2000
	s_add_u32 s22, s26, 0x160000
	v_lshl_add_u64 v[188:189], s[26:27], 0, v[194:195]
	s_addc_u32 s23, s27, 0
	s_add_i32 s50, s51, s2
	global_load_lds_dwordx4 v[188:189], off
	v_lshl_add_u64 v[190:191], s[22:23], 0, v[0:1]
	s_mov_b32 m0, s50
	v_lshl_add_u64 v[192:193], s[28:29], 0, v[196:197]
	global_load_lds_dwordx4 v[190:191], off
	v_lshl_add_u64 v[190:191], s[22:23], 0, v[194:195]
	s_add_i32 m0, s50, 0x2000
	s_nop 0
	global_load_lds_dwordx4 v[190:191], off
	v_lshl_add_u64 v[190:191], s[28:29], 0, v[198:199]
	s_mov_b32 m0, s6
	s_nop 0
	global_load_lds_dwordx4 v[190:191], off
	s_mov_b32 m0, s7
	s_nop 0
	global_load_lds_dwordx4 v[192:193], off
	s_waitcnt vmcnt(8)
	s_waitcnt lgkmcnt(0)
	s_barrier
; #define PG8_STAGE(bufoff, gbase, voff) do { _Pragma("unroll") for (int _i = 0; _i < 2; ++_i) \
;         __builtin_amdgcn_global_load_lds((const unsigned*)((const char*)(gbase) + (voff)[_i]), (LAS unsigned*)(lds + (bufoff) + ldsw + _i * 8192), 16, 0, 0); } while (0)
; #define PG8_LDA(dst, b, h) do { _Pragma("unroll") for (int m = 0; m < 4; ++m) _Pragma("unroll") for (int k = 0; k < 2; ++k) dst[m][k] = *(const LAS bf16x8*)(lds + PG8_SA(b, h) + aoff + m * 2048 + k * 1024); } while (0)
; #define PG8_LDB(dst, b, h) do { _Pragma("unroll") for (int n = 0; n < 2; ++n) _Pragma("unroll") for (int k = 0; k < 2; ++k) dst[n][k] = *(const LAS bf16x8*)(lds + PG8_SB(b, h) + boff + n * 2048 + k * 1024); } while (0)
; #define PG8_MMA(ai, bj, At, Bt) do { __builtin_amdgcn_s_setprio(1); _Pragma("unroll") for (int m = 0; m < 4; ++m) _Pragma("unroll") for (int n = 0; n < 2; ++n) _Pragma("unroll") for (int k = 0; k < 2; ++k) \
;         acc[ai][bj][m][n] = __builtin_amdgcn_mfma_f32_16x16x32_bf16(Bt[n][k], At[m][k], acc[ai][bj][m][n], 0, 0, 0); __builtin_amdgcn_s_setprio(0); } while (0)
; #define PG8_WAIT_V(n) asm volatile("s_waitcnt vmcnt(" #n ")" ::: "memory")
; #define PG8_WAIT_L(n) asm volatile("s_waitcnt lgkmcnt(" #n ")" ::: "memory")
; #define PG8_BAR __builtin_amdgcn_s_barrier()
; #define PG8_SCHED __builtin_amdgcn_sched_barrier(0)
; template <class Epi, class Sched, bool ALIGN_EPI = false, bool SP2 = false>
; __device__ __forceinline__ void gemm_phase(LAS unsigned char* lds, const Gemm g, const Sched& S, const Epi& E) {
;     ...
;             PG8_WAIT_V(8); PG8_WAIT_L(0); PG8_BAR; PG8_MMA(1, 0, At, B0); PG8_MMA(1, 1, At, B1); PG8_BAR; PG8_SCHED;
;             PG8_LDB(B0, 1, 0); PG8_LDB(B1, 1, 1); PG8_SCHED; PG8_LDA(At, 1, 0); PG8_STAGE(PG8_SA(0, 1), a2 + hstep, voffA);
;             PG8_WAIT_V(8); PG8_WAIT_L(0); PG8_BAR; PG8_MMA(0, 0, At, B0); PG8_MMA(0, 1, At, B1); PG8_BAR; PG8_SCHED;
	s_setprio 1
	s_waitcnt lgkmcnt(0)
	v_mfma_f32_16x16x32_bf16 v[62:65], v[90:93], v[162:165], v[62:65]
	v_mfma_f32_16x16x32_bf16 v[62:65], v[102:105], v[166:169], v[62:65]
	v_mfma_f32_16x16x32_bf16 v[58:61], v[114:117], v[162:165], v[58:61]
	v_mfma_f32_16x16x32_bf16 v[58:61], v[126:129], v[166:169], v[58:61]
	v_mfma_f32_16x16x32_bf16 v[42:45], v[114:117], v[170:173], v[42:45]
	v_mfma_f32_16x16x32_bf16 v[42:45], v[126:129], v[174:177], v[42:45]
	v_mfma_f32_16x16x32_bf16 v[46:49], v[90:93], v[170:173], v[46:49]
	v_mfma_f32_16x16x32_bf16 v[46:49], v[102:105], v[174:177], v[46:49]
	v_mfma_f32_16x16x32_bf16 v[30:33], v[90:93], v[178:181], v[30:33]
	v_mfma_f32_16x16x32_bf16 v[30:33], v[102:105], v[182:185], v[30:33]
	v_mfma_f32_16x16x32_bf16 v[26:29], v[114:117], v[178:181], v[26:29]
	v_mfma_f32_16x16x32_bf16 v[26:29], v[126:129], v[182:185], v[26:29]
	v_mfma_f32_16x16x32_bf16 v[10:13], v[114:117], v[204:207], v[10:13]
	v_mfma_f32_16x16x32_bf16 v[10:13], v[126:129], v[208:211], v[10:13]
	v_mfma_f32_16x16x32_bf16 v[14:17], v[90:93], v[204:207], v[14:17]
	v_mfma_f32_16x16x32_bf16 v[14:17], v[102:105], v[208:211], v[14:17]
	s_setprio 0
	s_setprio 1
	v_mfma_f32_16x16x32_bf16 v[54:57], v[138:141], v[162:165], v[54:57]
	v_mfma_f32_16x16x32_bf16 v[54:57], v[142:145], v[166:169], v[54:57]
	v_mfma_f32_16x16x32_bf16 v[50:53], v[154:157], v[162:165], v[50:53]
	v_mfma_f32_16x16x32_bf16 v[50:53], v[158:161], v[166:169], v[50:53]
	v_mfma_f32_16x16x32_bf16 v[34:37], v[154:157], v[170:173], v[34:37]
	v_mfma_f32_16x16x32_bf16 v[34:37], v[158:161], v[174:177], v[34:37]
	v_mfma_f32_16x16x32_bf16 v[38:41], v[138:141], v[170:173], v[38:41]
	v_mfma_f32_16x16x32_bf16 v[38:41], v[142:145], v[174:177], v[38:41]
	v_mfma_f32_16x16x32_bf16 v[22:25], v[138:141], v[178:181], v[22:25]
	v_mfma_f32_16x16x32_bf16 v[22:25], v[142:145], v[182:185], v[22:25]
	v_mfma_f32_16x16x32_bf16 v[18:21], v[154:157], v[178:181], v[18:21]
	v_mfma_f32_16x16x32_bf16 v[18:21], v[158:161], v[182:185], v[18:21]
	v_mfma_f32_16x16x32_bf16 v[2:5], v[154:157], v[204:207], v[2:5]
	v_mfma_f32_16x16x32_bf16 v[2:5], v[158:161], v[208:211], v[2:5]
	v_mfma_f32_16x16x32_bf16 v[6:9], v[138:141], v[204:207], v[6:9]
	v_mfma_f32_16x16x32_bf16 v[6:9], v[142:145], v[208:211], v[6:9]
	s_setprio 0
	s_barrier
	s_add_i32 s50, 0, 0x18000
	s_add_i32 s51, 0, 0x1c000
	v_add_u32_e32 v126, s50, v247
	v_add_u32_e32 v158, s51, v247
	ds_read_b128 v[90:93], v126
	ds_read_b128 v[102:105], v126 offset:1024
	ds_read_b128 v[114:117], v126 offset:2048
	ds_read_b128 v[126:129], v126 offset:3072
	ds_read_b128 v[138:141], v158
	ds_read_b128 v[142:145], v158 offset:1024
	ds_read_b128 v[154:157], v158 offset:2048
	ds_read_b128 v[158:161], v158 offset:3072
	s_add_u32 s22, s28, 0x160000
	s_addc_u32 s23, s29, 0
	s_mov_b32 m0, s8
	v_lshl_add_u64 v[212:213], s[22:23], 0, v[198:199]
	ds_read_b128 v[162:165], v249 offset:32768
	ds_read_b128 v[166:169], v249 offset:33792
	ds_read_b128 v[170:173], v249 offset:34816
	ds_read_b128 v[174:177], v249 offset:35840
	ds_read_b128 v[178:181], v249 offset:36864
	ds_read_b128 v[182:185], v249 offset:37888
	ds_read_b128 v[204:207], v249 offset:38912
	ds_read_b128 v[208:211], v249 offset:39936
	global_load_lds_dwordx4 v[212:213], off
	v_lshl_add_u64 v[212:213], s[22:23], 0, v[196:197]
	s_mov_b32 m0, s31
	s_nop 0
	global_load_lds_dwordx4 v[212:213], off
	s_waitcnt vmcnt(8)
	s_waitcnt lgkmcnt(0)
	s_barrier
	s_setprio 1
	s_waitcnt lgkmcnt(0)
	v_mfma_f32_16x16x32_bf16 v[150:153], v[90:93], v[162:165], v[150:153]
	v_mfma_f32_16x16x32_bf16 v[150:153], v[102:105], v[166:169], v[150:153]
	v_mfma_f32_16x16x32_bf16 v[146:149], v[114:117], v[162:165], v[146:149]
	v_mfma_f32_16x16x32_bf16 v[146:149], v[126:129], v[166:169], v[146:149]
	v_mfma_f32_16x16x32_bf16 v[118:121], v[114:117], v[170:173], v[118:121]
	v_mfma_f32_16x16x32_bf16 v[118:121], v[126:129], v[174:177], v[118:121]
	v_mfma_f32_16x16x32_bf16 v[122:125], v[90:93], v[170:173], v[122:125]
	v_mfma_f32_16x16x32_bf16 v[122:125], v[102:105], v[174:177], v[122:125]
	v_mfma_f32_16x16x32_bf16 v[98:101], v[90:93], v[178:181], v[98:101]
	v_mfma_f32_16x16x32_bf16 v[98:101], v[102:105], v[182:185], v[98:101]
	v_mfma_f32_16x16x32_bf16 v[94:97], v[114:117], v[178:181], v[94:97]
	v_mfma_f32_16x16x32_bf16 v[94:97], v[126:129], v[182:185], v[94:97]
	v_mfma_f32_16x16x32_bf16 v[74:77], v[114:117], v[204:207], v[74:77]
	v_mfma_f32_16x16x32_bf16 v[74:77], v[126:129], v[208:211], v[74:77]
	v_mfma_f32_16x16x32_bf16 v[78:81], v[90:93], v[204:207], v[78:81]
	v_mfma_f32_16x16x32_bf16 v[78:81], v[102:105], v[208:211], v[78:81]
	s_setprio 0
	s_setprio 1
	v_mfma_f32_16x16x32_bf16 v[134:137], v[138:141], v[162:165], v[134:137]
	v_mfma_f32_16x16x32_bf16 v[134:137], v[142:145], v[166:169], v[134:137]
	v_mfma_f32_16x16x32_bf16 v[130:133], v[154:157], v[162:165], v[130:133]
	v_mfma_f32_16x16x32_bf16 v[130:133], v[158:161], v[166:169], v[130:133]
	v_mfma_f32_16x16x32_bf16 v[106:109], v[154:157], v[170:173], v[106:109]
	v_mfma_f32_16x16x32_bf16 v[106:109], v[158:161], v[174:177], v[106:109]
	v_mfma_f32_16x16x32_bf16 v[110:113], v[138:141], v[170:173], v[110:113]
	v_mfma_f32_16x16x32_bf16 v[110:113], v[142:145], v[174:177], v[110:113]
	v_mfma_f32_16x16x32_bf16 v[86:89], v[138:141], v[178:181], v[86:89]
	v_mfma_f32_16x16x32_bf16 v[86:89], v[142:145], v[182:185], v[86:89]
	v_mfma_f32_16x16x32_bf16 v[82:85], v[154:157], v[178:181], v[82:85]
	v_mfma_f32_16x16x32_bf16 v[82:85], v[158:161], v[182:185], v[82:85]
	v_mfma_f32_16x16x32_bf16 v[66:69], v[154:157], v[204:207], v[66:69]
	v_mfma_f32_16x16x32_bf16 v[66:69], v[158:161], v[208:211], v[66:69]
	v_mfma_f32_16x16x32_bf16 v[70:73], v[138:141], v[204:207], v[70:73]
	v_mfma_f32_16x16x32_bf16 v[70:73], v[142:145], v[208:211], v[70:73]
	s_setprio 0
	s_barrier
; #define PG8_STAGE(bufoff, gbase, voff) do { _Pragma("unroll") for (int _i = 0; _i < 2; ++_i) \
;         __builtin_amdgcn_global_load_lds((const unsigned*)((const char*)(gbase) + (voff)[_i]), (LAS unsigned*)(lds + (bufoff) + ldsw + _i * 8192), 16, 0, 0); } while (0)
; #define PG8_LDA(dst, b, h) do { _Pragma("unroll") for (int m = 0; m < 4; ++m) _Pragma("unroll") for (int k = 0; k < 2; ++k) dst[m][k] = *(const LAS bf16x8*)(lds + PG8_SA(b, h) + aoff + m * 2048 + k * 1024); } while (0)
; #define PG8_MMA(ai, bj, At, Bt) do { __builtin_amdgcn_s_setprio(1); _Pragma("unroll") for (int m = 0; m < 4; ++m) _Pragma("unroll") for (int n = 0; n < 2; ++n) _Pragma("unroll") for (int k = 0; k < 2; ++k) \
;         acc[ai][bj][m][n] = __builtin_amdgcn_mfma_f32_16x16x32_bf16(Bt[n][k], At[m][k], acc[ai][bj][m][n], 0, 0, 0); __builtin_amdgcn_s_setprio(0); } while (0)
; #define PG8_WAIT_V(n) asm volatile("s_waitcnt vmcnt(" #n ")" ::: "memory")
; #define PG8_WAIT_L(n) asm volatile("s_waitcnt lgkmcnt(" #n ")" ::: "memory")
; #define PG8_BAR __builtin_amdgcn_s_barrier()
; #define PG8_SCHED __builtin_amdgcn_sched_barrier(0)
; template <class Epi, class Sched, bool ALIGN_EPI = false, bool SP2 = false>
; __device__ __forceinline__ void gemm_phase(LAS unsigned char* lds, const Gemm g, const Sched& S, const Epi& E) {
;     ...
;             PG8_LDA(At, 1, 1); PG8_STAGE(PG8_SB(1, 0), b3, voffB); PG8_STAGE(PG8_SB(1, 1), b3 + hstep, voffB); PG8_STAGE(PG8_SA(1, 0), a3, voffA);
;             PG8_WAIT_V(8); PG8_WAIT_L(0); PG8_BAR; PG8_MMA(1, 0, At, B0); PG8_MMA(1, 1, At, B1); PG8_BAR; PG8_SCHED;
	s_add_i32 s22, s50, s2
	v_lshl_add_u64 v[186:187], v[186:187], 0, s[12:13]
	s_mov_b32 m0, s22
	ds_read_b128 v[162:165], v249 offset:49152
	ds_read_b128 v[166:169], v249 offset:50176
	ds_read_b128 v[170:173], v249 offset:51200
	ds_read_b128 v[174:177], v249 offset:52224
	ds_read_b128 v[178:181], v249 offset:53248
	ds_read_b128 v[182:185], v249 offset:54272
	ds_read_b128 v[204:207], v249 offset:55296
	ds_read_b128 v[208:211], v249 offset:56320
	global_load_lds_dwordx4 v[186:187], off
	s_add_i32 m0, s22, 0x2000
	s_add_u32 s22, s26, 0x160080
	v_lshl_add_u64 v[186:187], v[188:189], 0, s[12:13]
	s_addc_u32 s23, s27, 0
	s_add_i32 s26, s51, s2
	global_load_lds_dwordx4 v[186:187], off
	v_lshl_add_u64 v[186:187], s[22:23], 0, v[0:1]
	s_mov_b32 m0, s26
	s_nop 0
	global_load_lds_dwordx4 v[186:187], off
	v_lshl_add_u64 v[186:187], s[22:23], 0, v[194:195]
	s_add_i32 m0, s26, 0x2000
	s_nop 0
	global_load_lds_dwordx4 v[186:187], off
	v_lshl_add_u64 v[186:187], v[190:191], 0, s[12:13]
	s_mov_b32 m0, s35
	s_nop 0
	global_load_lds_dwordx4 v[186:187], off
	v_lshl_add_u64 v[186:187], v[192:193], 0, s[12:13]
	s_mov_b32 m0, s40
	s_nop 0
	global_load_lds_dwordx4 v[186:187], off
	s_waitcnt vmcnt(8)
	s_waitcnt lgkmcnt(0)
	s_barrier
	s_setprio 1
	s_waitcnt lgkmcnt(0)
	v_mfma_f32_16x16x32_bf16 v[62:65], v[90:93], v[162:165], v[62:65]
	v_mfma_f32_16x16x32_bf16 v[62:65], v[102:105], v[166:169], v[62:65]
	v_mfma_f32_16x16x32_bf16 v[58:61], v[114:117], v[162:165], v[58:61]
	v_mfma_f32_16x16x32_bf16 v[58:61], v[126:129], v[166:169], v[58:61]
	v_mfma_f32_16x16x32_bf16 v[42:45], v[114:117], v[170:173], v[42:45]
	v_mfma_f32_16x16x32_bf16 v[42:45], v[126:129], v[174:177], v[42:45]
	v_mfma_f32_16x16x32_bf16 v[46:49], v[90:93], v[170:173], v[46:49]
	v_mfma_f32_16x16x32_bf16 v[46:49], v[102:105], v[174:177], v[46:49]
	v_mfma_f32_16x16x32_bf16 v[30:33], v[90:93], v[178:181], v[30:33]
	v_mfma_f32_16x16x32_bf16 v[30:33], v[102:105], v[182:185], v[30:33]
	v_mfma_f32_16x16x32_bf16 v[26:29], v[114:117], v[178:181], v[26:29]
	v_mfma_f32_16x16x32_bf16 v[26:29], v[126:129], v[182:185], v[26:29]
	v_mfma_f32_16x16x32_bf16 v[10:13], v[114:117], v[204:207], v[10:13]
	v_mfma_f32_16x16x32_bf16 v[10:13], v[126:129], v[208:211], v[10:13]
	v_mfma_f32_16x16x32_bf16 v[14:17], v[90:93], v[204:207], v[14:17]
	v_mfma_f32_16x16x32_bf16 v[14:17], v[102:105], v[208:211], v[14:17]
	s_setprio 0
	s_setprio 1
	v_mfma_f32_16x16x32_bf16 v[54:57], v[138:141], v[162:165], v[54:57]
	v_mfma_f32_16x16x32_bf16 v[54:57], v[142:145], v[166:169], v[54:57]
	v_mfma_f32_16x16x32_bf16 v[50:53], v[154:157], v[162:165], v[50:53]
	v_mfma_f32_16x16x32_bf16 v[50:53], v[158:161], v[166:169], v[50:53]
	v_mfma_f32_16x16x32_bf16 v[34:37], v[154:157], v[170:173], v[34:37]
	v_mfma_f32_16x16x32_bf16 v[34:37], v[158:161], v[174:177], v[34:37]
	v_mfma_f32_16x16x32_bf16 v[38:41], v[138:141], v[170:173], v[38:41]
	v_mfma_f32_16x16x32_bf16 v[38:41], v[142:145], v[174:177], v[38:41]
	v_mfma_f32_16x16x32_bf16 v[22:25], v[138:141], v[178:181], v[22:25]
	v_mfma_f32_16x16x32_bf16 v[22:25], v[142:145], v[182:185], v[22:25]
	v_mfma_f32_16x16x32_bf16 v[18:21], v[154:157], v[178:181], v[18:21]
	v_mfma_f32_16x16x32_bf16 v[18:21], v[158:161], v[182:185], v[18:21]
	v_mfma_f32_16x16x32_bf16 v[2:5], v[154:157], v[204:207], v[2:5]
	v_mfma_f32_16x16x32_bf16 v[2:5], v[158:161], v[208:211], v[2:5]
	v_mfma_f32_16x16x32_bf16 v[6:9], v[138:141], v[204:207], v[6:9]
	v_mfma_f32_16x16x32_bf16 v[6:9], v[142:145], v[208:211], v[6:9]
	s_setprio 0
	s_barrier
	s_add_i32 s49, s49, 2
	s_add_u32 s47, s47, 0x100
	s_addc_u32 s48, s48, 0
	s_cmpk_gt_u32 s49, 0x55
	s_mov_b64 s[22:23], s[24:25]
	s_cbranch_scc0 .LBB0_257
	s_and_b64 vcc, exec, s[18:19]
	s_cbranch_vccz .LBB0_260
	s_barrier

; #define PG8_STAGE(bufoff, gbase, voff) do { _Pragma("unroll") for (int _i = 0; _i < 2; ++_i) \
;         __builtin_amdgcn_global_load_lds((const unsigned*)((const char*)(gbase) + (voff)[_i]), (LAS unsigned*)(lds + (bufoff) + ldsw + _i * 8192), 16, 0, 0); } while (0)
; #define PG8_LDA(dst, b, h) do { _Pragma("unroll") for (int m = 0; m < 4; ++m) _Pragma("unroll") for (int k = 0; k < 2; ++k) dst[m][k] = *(const LAS bf16x8*)(lds + PG8_SA(b, h) + aoff + m * 2048 + k * 1024); } while (0)
; #define PG8_LDB(dst, b, h) do { _Pragma("unroll") for (int n = 0; n < 2; ++n) _Pragma("unroll") for (int k = 0; k < 2; ++k) dst[n][k] = *(const LAS bf16x8*)(lds + PG8_SB(b, h) + boff + n * 2048 + k * 1024); } while (0)
; #define PG8_WAIT_V(n) asm volatile("s_waitcnt vmcnt(" #n ")" ::: "memory")
; #define PG8_WAIT_L(n) asm volatile("s_waitcnt lgkmcnt(" #n ")" ::: "memory")
; #define PG8_BAR __builtin_amdgcn_s_barrier()
; #define PG8_SCHED __builtin_amdgcn_sched_barrier(0)
; template <class Epi, class Sched, bool ALIGN_EPI = false, bool SP2 = false>
; __device__ __forceinline__ void gemm_phase(LAS unsigned char* lds, const Gemm g, const Sched& S, const Epi& E) {
;     ...
;         const bool has_next = S.next(ui + 1, nxt);
;         const char* nA = has_next ? (const char*)g.A + (size_t)nxt.pm * tstep : cA; const char* nB = has_next ? (const char*)g.Bt + (size_t)nxt.pn * tstep : cB;
;         for (int t = 0; t < nt; t += 2) {
;             const bool last = (t == nt - 2);
;             const char* a1 = cA + (size_t)(t + 1) * kstep;
;             const char* a2 = last ? nA : cA + (size_t)(t + 2) * kstep; const char* b2 = last ? nB : cB + (size_t)(t + 2) * kstep;
;             const char* a3 = a2 + kstep; const char* b3 = b2 + kstep;
;             if (last && has_next) S.a_ready(nxt);
;             if constexpr (SP2) {
;             PG8_LDB(B0, 0, 0); PG8_LDB(B1, 0, 1); PG8_SCHED; PG8_LDA(At, 0, 0); PG8_STAGE(PG8_SA(1, 1), a1 + hstep, voffA);
;             PG8_WAIT_V(8); PG8_WAIT_L(0); PG8_BAR; PG8_MMA(0, 0, At, B0); PG8_MMA(0, 1, At, B1); PG8_BAR; PG8_SCHED;
;             PG8_LDA(At, 0, 1); PG8_STAGE(PG8_SB(0, 0), b2, voffB); PG8_STAGE(PG8_SB(0, 1), b2 + hstep, voffB); PG8_STAGE(PG8_SA(0, 0), a2, voffA);
;             PG8_WAIT_V(8); PG8_WAIT_L(0); PG8_BAR; PG8_MMA(1, 0, At, B0); PG8_MMA(1, 1, At, B1); PG8_BAR; PG8_SCHED;
.LBB0_359:
	s_add_u32 s28, s26, 0xfff80080
	s_addc_u32 s29, s27, -1
	s_add_i32 s41, 0, 0x10000
	s_cmp_eq_u32 s40, 28
	s_cselect_b32 s31, s6, s29
	s_cselect_b32 s30, s7, s28
	v_add_u32_e32 v0, s41, v159
	s_cselect_b32 s29, s8, s35
	s_cselect_b32 s28, s19, s21
	s_add_i32 s57, 0, 0x14000
	ds_read_b128 v[142:145], v0
	ds_read_b128 v[146:149], v0 offset:1024
	ds_read_b128 v[150:153], v0 offset:2048
	ds_read_b128 v[154:157], v0 offset:3072
	v_add_u32_e32 v0, s57, v159
	ds_read_b128 v[162:165], v0
	ds_read_b128 v[166:169], v0 offset:1024
	ds_read_b128 v[170:173], v0 offset:2048
	ds_read_b128 v[174:177], v0 offset:3072
	v_lshl_add_u64 v[210:211], s[26:27], 0, v[138:139]
	s_add_i32 m0, s44, 0xc000
	ds_read_b128 v[178:181], v161
	ds_read_b128 v[182:185], v161 offset:1024
	ds_read_b128 v[186:189], v161 offset:2048
	ds_read_b128 v[190:193], v161 offset:3072
	ds_read_b128 v[194:197], v161 offset:4096
	ds_read_b128 v[198:201], v161 offset:5120
	ds_read_b128 v[202:205], v161 offset:6144
	ds_read_b128 v[206:209], v161 offset:7168
	global_load_lds_dwordx4 v[210:211], off
	v_lshl_add_u64 v[210:211], s[26:27], 0, v[140:141]
	s_add_i32 m0, s44, 0xe000
	s_nop 0
	global_load_lds_dwordx4 v[210:211], off
	s_waitcnt vmcnt(8)
	s_waitcnt lgkmcnt(0)
	s_barrier
	s_setprio 1
	s_waitcnt lgkmcnt(0)
	v_mfma_f32_16x16x32_bf16 v[126:129], v[142:145], v[178:181], v[126:129]
	v_mfma_f32_16x16x32_bf16 v[126:129], v[146:149], v[182:185], v[126:129]
	v_mfma_f32_16x16x32_bf16 v[122:125], v[150:153], v[178:181], v[122:125]
	v_mfma_f32_16x16x32_bf16 v[122:125], v[154:157], v[182:185], v[122:125]
	v_mfma_f32_16x16x32_bf16 v[106:109], v[150:153], v[186:189], v[106:109]
	v_mfma_f32_16x16x32_bf16 v[106:109], v[154:157], v[190:193], v[106:109]
	v_mfma_f32_16x16x32_bf16 v[110:113], v[142:145], v[186:189], v[110:113]
	v_mfma_f32_16x16x32_bf16 v[110:113], v[146:149], v[190:193], v[110:113]
	v_mfma_f32_16x16x32_bf16 v[94:97], v[142:145], v[194:197], v[94:97]
	v_mfma_f32_16x16x32_bf16 v[94:97], v[146:149], v[198:201], v[94:97]
	v_mfma_f32_16x16x32_bf16 v[90:93], v[150:153], v[194:197], v[90:93]
	v_mfma_f32_16x16x32_bf16 v[90:93], v[154:157], v[198:201], v[90:93]
	v_mfma_f32_16x16x32_bf16 v[74:77], v[150:153], v[202:205], v[74:77]
	v_mfma_f32_16x16x32_bf16 v[74:77], v[154:157], v[206:209], v[74:77]
	v_mfma_f32_16x16x32_bf16 v[78:81], v[142:145], v[202:205], v[78:81]
	v_mfma_f32_16x16x32_bf16 v[78:81], v[146:149], v[206:209], v[78:81]
	s_setprio 0
	s_setprio 1
	v_mfma_f32_16x16x32_bf16 v[118:121], v[162:165], v[178:181], v[118:121]
	v_mfma_f32_16x16x32_bf16 v[118:121], v[166:169], v[182:185], v[118:121]
	v_mfma_f32_16x16x32_bf16 v[114:117], v[170:173], v[178:181], v[114:117]
	v_mfma_f32_16x16x32_bf16 v[114:117], v[174:177], v[182:185], v[114:117]
	v_mfma_f32_16x16x32_bf16 v[98:101], v[170:173], v[186:189], v[98:101]
	v_mfma_f32_16x16x32_bf16 v[98:101], v[174:177], v[190:193], v[98:101]
	v_mfma_f32_16x16x32_bf16 v[102:105], v[162:165], v[186:189], v[102:105]
	v_mfma_f32_16x16x32_bf16 v[102:105], v[166:169], v[190:193], v[102:105]
	v_mfma_f32_16x16x32_bf16 v[86:89], v[162:165], v[194:197], v[86:89]
	v_mfma_f32_16x16x32_bf16 v[86:89], v[166:169], v[198:201], v[86:89]
	v_mfma_f32_16x16x32_bf16 v[82:85], v[170:173], v[194:197], v[82:85]
	v_mfma_f32_16x16x32_bf16 v[82:85], v[174:177], v[198:201], v[82:85]
	v_mfma_f32_16x16x32_bf16 v[66:69], v[170:173], v[202:205], v[66:69]
	v_mfma_f32_16x16x32_bf16 v[66:69], v[174:177], v[206:209], v[66:69]
	v_mfma_f32_16x16x32_bf16 v[70:73], v[162:165], v[202:205], v[70:73]
	v_mfma_f32_16x16x32_bf16 v[70:73], v[166:169], v[206:209], v[70:73]
	s_setprio 0
	s_barrier
	s_add_i32 s41, s41, s9
	v_lshl_add_u64 v[210:211], s[28:29], 0, v[134:135]
	s_mov_b32 m0, s41
	ds_read_b128 v[178:181], v161 offset:16384
	ds_read_b128 v[182:185], v161 offset:17408
	ds_read_b128 v[186:189], v161 offset:18432
	ds_read_b128 v[190:193], v161 offset:19456
	ds_read_b128 v[194:197], v161 offset:20480
	ds_read_b128 v[198:201], v161 offset:21504
	ds_read_b128 v[202:205], v161 offset:22528
	ds_read_b128 v[206:209], v161 offset:23552
	global_load_lds_dwordx4 v[210:211], off
	s_add_i32 m0, s41, 0x2000
	s_add_u32 s58, s28, 0x80000
	v_lshl_add_u64 v[212:213], s[28:29], 0, v[130:131]
	s_addc_u32 s59, s29, 0
	s_add_i32 s41, s57, s9
	global_load_lds_dwordx4 v[212:213], off
	v_lshl_add_u64 v[214:215], s[58:59], 0, v[134:135]
	s_mov_b32 m0, s41
	v_lshl_add_u64 v[216:217], s[30:31], 0, v[132:133]
	global_load_lds_dwordx4 v[214:215], off
	v_lshl_add_u64 v[214:215], s[58:59], 0, v[130:131]
	s_add_i32 m0, s41, 0x2000
	s_nop 0
	global_load_lds_dwordx4 v[214:215], off
	v_lshl_add_u64 v[214:215], s[30:31], 0, v[136:137]
	s_mov_b32 m0, s44
	s_nop 0
	global_load_lds_dwordx4 v[214:215], off
	s_mov_b32 m0, s45
	s_nop 0
	global_load_lds_dwordx4 v[216:217], off
	s_waitcnt vmcnt(8)
	s_waitcnt lgkmcnt(0)
	s_barrier
; #define PG8_STAGE(bufoff, gbase, voff) do { _Pragma("unroll") for (int _i = 0; _i < 2; ++_i) \
;         __builtin_amdgcn_global_load_lds((const unsigned*)((const char*)(gbase) + (voff)[_i]), (LAS unsigned*)(lds + (bufoff) + ldsw + _i * 8192), 16, 0, 0); } while (0)
; #define PG8_LDA(dst, b, h) do { _Pragma("unroll") for (int m = 0; m < 4; ++m) _Pragma("unroll") for (int k = 0; k < 2; ++k) dst[m][k] = *(const LAS bf16x8*)(lds + PG8_SA(b, h) + aoff + m * 2048 + k * 1024); } while (0)
; #define PG8_LDB(dst, b, h) do { _Pragma("unroll") for (int n = 0; n < 2; ++n) _Pragma("unroll") for (int k = 0; k < 2; ++k) dst[n][k] = *(const LAS bf16x8*)(lds + PG8_SB(b, h) + boff + n * 2048 + k * 1024); } while (0)
; #define PG8_MMA(ai, bj, At, Bt) do { __builtin_amdgcn_s_setprio(1); _Pragma("unroll") for (int m = 0; m < 4; ++m) _Pragma("unroll") for (int n = 0; n < 2; ++n) _Pragma("unroll") for (int k = 0; k < 2; ++k) \
;         acc[ai][bj][m][n] = __builtin_amdgcn_mfma_f32_16x16x32_bf16(Bt[n][k], At[m][k], acc[ai][bj][m][n], 0, 0, 0); __builtin_amdgcn_s_setprio(0); } while (0)
; #define PG8_WAIT_V(n) asm volatile("s_waitcnt vmcnt(" #n ")" ::: "memory")
; #define PG8_WAIT_L(n) asm volatile("s_waitcnt lgkmcnt(" #n ")" ::: "memory")
; #define PG8_BAR __builtin_amdgcn_s_barrier()
; #define PG8_SCHED __builtin_amdgcn_sched_barrier(0)
; template <class Epi, class Sched, bool ALIGN_EPI = false, bool SP2 = false>
; __device__ __forceinline__ void gemm_phase(LAS unsigned char* lds, const Gemm g, const Sched& S, const Epi& E) {
;     ...
;             PG8_WAIT_V(8); PG8_WAIT_L(0); PG8_BAR; PG8_MMA(1, 0, At, B0); PG8_MMA(1, 1, At, B1); PG8_BAR; PG8_SCHED;
;             PG8_LDB(B0, 1, 0); PG8_LDB(B1, 1, 1); PG8_SCHED; PG8_LDA(At, 1, 0); PG8_STAGE(PG8_SA(0, 1), a2 + hstep, voffA);
;             PG8_WAIT_V(8); PG8_WAIT_L(0); PG8_BAR; PG8_MMA(0, 0, At, B0); PG8_MMA(0, 1, At, B1); PG8_BAR; PG8_SCHED;
	s_setprio 1
	s_waitcnt lgkmcnt(0)
	v_mfma_f32_16x16x32_bf16 v[62:65], v[142:145], v[178:181], v[62:65]
	v_mfma_f32_16x16x32_bf16 v[62:65], v[146:149], v[182:185], v[62:65]
	v_mfma_f32_16x16x32_bf16 v[58:61], v[150:153], v[178:181], v[58:61]
	v_mfma_f32_16x16x32_bf16 v[58:61], v[154:157], v[182:185], v[58:61]
	v_mfma_f32_16x16x32_bf16 v[42:45], v[150:153], v[186:189], v[42:45]
	v_mfma_f32_16x16x32_bf16 v[42:45], v[154:157], v[190:193], v[42:45]
	v_mfma_f32_16x16x32_bf16 v[46:49], v[142:145], v[186:189], v[46:49]
	v_mfma_f32_16x16x32_bf16 v[46:49], v[146:149], v[190:193], v[46:49]
	v_mfma_f32_16x16x32_bf16 v[30:33], v[142:145], v[194:197], v[30:33]
	v_mfma_f32_16x16x32_bf16 v[30:33], v[146:149], v[198:201], v[30:33]
	v_mfma_f32_16x16x32_bf16 v[26:29], v[150:153], v[194:197], v[26:29]
	v_mfma_f32_16x16x32_bf16 v[26:29], v[154:157], v[198:201], v[26:29]
	v_mfma_f32_16x16x32_bf16 v[10:13], v[150:153], v[202:205], v[10:13]
	v_mfma_f32_16x16x32_bf16 v[10:13], v[154:157], v[206:209], v[10:13]
	v_mfma_f32_16x16x32_bf16 v[14:17], v[142:145], v[202:205], v[14:17]
	v_mfma_f32_16x16x32_bf16 v[14:17], v[146:149], v[206:209], v[14:17]
	s_setprio 0
	s_setprio 1
	v_mfma_f32_16x16x32_bf16 v[54:57], v[162:165], v[178:181], v[54:57]
	v_mfma_f32_16x16x32_bf16 v[54:57], v[166:169], v[182:185], v[54:57]
	v_mfma_f32_16x16x32_bf16 v[50:53], v[170:173], v[178:181], v[50:53]
	v_mfma_f32_16x16x32_bf16 v[50:53], v[174:177], v[182:185], v[50:53]
	v_mfma_f32_16x16x32_bf16 v[34:37], v[170:173], v[186:189], v[34:37]
	v_mfma_f32_16x16x32_bf16 v[34:37], v[174:177], v[190:193], v[34:37]
	v_mfma_f32_16x16x32_bf16 v[38:41], v[162:165], v[186:189], v[38:41]
	v_mfma_f32_16x16x32_bf16 v[38:41], v[166:169], v[190:193], v[38:41]
	v_mfma_f32_16x16x32_bf16 v[22:25], v[162:165], v[194:197], v[22:25]
	v_mfma_f32_16x16x32_bf16 v[22:25], v[166:169], v[198:201], v[22:25]
	v_mfma_f32_16x16x32_bf16 v[18:21], v[170:173], v[194:197], v[18:21]
	v_mfma_f32_16x16x32_bf16 v[18:21], v[174:177], v[198:201], v[18:21]
	v_mfma_f32_16x16x32_bf16 v[2:5], v[170:173], v[202:205], v[2:5]
	v_mfma_f32_16x16x32_bf16 v[2:5], v[174:177], v[206:209], v[2:5]
	v_mfma_f32_16x16x32_bf16 v[6:9], v[162:165], v[202:205], v[6:9]
	v_mfma_f32_16x16x32_bf16 v[6:9], v[166:169], v[206:209], v[6:9]
	s_setprio 0
	s_barrier
	s_add_i32 s41, 0, 0x18000
	v_add_u32_e32 v0, s41, v159
	s_add_i32 s57, 0, 0x1c000
	ds_read_b128 v[142:145], v0
	ds_read_b128 v[146:149], v0 offset:1024
	ds_read_b128 v[150:153], v0 offset:2048
	ds_read_b128 v[154:157], v0 offset:3072
	v_add_u32_e32 v0, s57, v159
	ds_read_b128 v[162:165], v0
	ds_read_b128 v[166:169], v0 offset:1024
	ds_read_b128 v[170:173], v0 offset:2048
	ds_read_b128 v[174:177], v0 offset:3072
	s_add_u32 s30, s30, 0x80000
	s_addc_u32 s31, s31, 0
	s_mov_b32 m0, s47
	v_lshl_add_u64 v[218:219], s[30:31], 0, v[136:137]
	ds_read_b128 v[178:181], v161 offset:32768
	ds_read_b128 v[182:185], v161 offset:33792
	ds_read_b128 v[186:189], v161 offset:34816
	ds_read_b128 v[190:193], v161 offset:35840
	ds_read_b128 v[194:197], v161 offset:36864
	ds_read_b128 v[198:201], v161 offset:37888
	ds_read_b128 v[202:205], v161 offset:38912
	ds_read_b128 v[206:209], v161 offset:39936
	global_load_lds_dwordx4 v[218:219], off
	v_lshl_add_u64 v[218:219], s[30:31], 0, v[132:133]
	s_mov_b32 m0, s48
	s_nop 0
	global_load_lds_dwordx4 v[218:219], off
	s_waitcnt vmcnt(8)
	s_waitcnt lgkmcnt(0)
	s_barrier
	s_setprio 1
	s_waitcnt lgkmcnt(0)
	v_mfma_f32_16x16x32_bf16 v[126:129], v[142:145], v[178:181], v[126:129]
	v_mfma_f32_16x16x32_bf16 v[126:129], v[146:149], v[182:185], v[126:129]
	v_mfma_f32_16x16x32_bf16 v[122:125], v[150:153], v[178:181], v[122:125]
	v_mfma_f32_16x16x32_bf16 v[122:125], v[154:157], v[182:185], v[122:125]
	v_mfma_f32_16x16x32_bf16 v[106:109], v[150:153], v[186:189], v[106:109]
	v_mfma_f32_16x16x32_bf16 v[106:109], v[154:157], v[190:193], v[106:109]
	v_mfma_f32_16x16x32_bf16 v[110:113], v[142:145], v[186:189], v[110:113]
	v_mfma_f32_16x16x32_bf16 v[110:113], v[146:149], v[190:193], v[110:113]
	v_mfma_f32_16x16x32_bf16 v[94:97], v[142:145], v[194:197], v[94:97]
	v_mfma_f32_16x16x32_bf16 v[94:97], v[146:149], v[198:201], v[94:97]
	v_mfma_f32_16x16x32_bf16 v[90:93], v[150:153], v[194:197], v[90:93]
	v_mfma_f32_16x16x32_bf16 v[90:93], v[154:157], v[198:201], v[90:93]
	v_mfma_f32_16x16x32_bf16 v[74:77], v[150:153], v[202:205], v[74:77]
	v_mfma_f32_16x16x32_bf16 v[74:77], v[154:157], v[206:209], v[74:77]
	v_mfma_f32_16x16x32_bf16 v[78:81], v[142:145], v[202:205], v[78:81]
	v_mfma_f32_16x16x32_bf16 v[78:81], v[146:149], v[206:209], v[78:81]
	s_setprio 0
	s_setprio 1
	v_mfma_f32_16x16x32_bf16 v[118:121], v[162:165], v[178:181], v[118:121]
	v_mfma_f32_16x16x32_bf16 v[118:121], v[166:169], v[182:185], v[118:121]
	v_mfma_f32_16x16x32_bf16 v[114:117], v[170:173], v[178:181], v[114:117]
	v_mfma_f32_16x16x32_bf16 v[114:117], v[174:177], v[182:185], v[114:117]
	v_mfma_f32_16x16x32_bf16 v[98:101], v[170:173], v[186:189], v[98:101]
	v_mfma_f32_16x16x32_bf16 v[98:101], v[174:177], v[190:193], v[98:101]
	v_mfma_f32_16x16x32_bf16 v[102:105], v[162:165], v[186:189], v[102:105]
	v_mfma_f32_16x16x32_bf16 v[102:105], v[166:169], v[190:193], v[102:105]
	v_mfma_f32_16x16x32_bf16 v[86:89], v[162:165], v[194:197], v[86:89]
	v_mfma_f32_16x16x32_bf16 v[86:89], v[166:169], v[198:201], v[86:89]
	v_mfma_f32_16x16x32_bf16 v[82:85], v[170:173], v[194:197], v[82:85]
	v_mfma_f32_16x16x32_bf16 v[82:85], v[174:177], v[198:201], v[82:85]
	v_mfma_f32_16x16x32_bf16 v[66:69], v[170:173], v[202:205], v[66:69]
	v_mfma_f32_16x16x32_bf16 v[66:69], v[174:177], v[206:209], v[66:69]
	v_mfma_f32_16x16x32_bf16 v[70:73], v[162:165], v[202:205], v[70:73]
	v_mfma_f32_16x16x32_bf16 v[70:73], v[166:169], v[206:209], v[70:73]
	s_setprio 0
	s_barrier
; #define PG8_STAGE(bufoff, gbase, voff) do { _Pragma("unroll") for (int _i = 0; _i < 2; ++_i) \
;         __builtin_amdgcn_global_load_lds((const unsigned*)((const char*)(gbase) + (voff)[_i]), (LAS unsigned*)(lds + (bufoff) + ldsw + _i * 8192), 16, 0, 0); } while (0)
; #define PG8_LDA(dst, b, h) do { _Pragma("unroll") for (int m = 0; m < 4; ++m) _Pragma("unroll") for (int k = 0; k < 2; ++k) dst[m][k] = *(const LAS bf16x8*)(lds + PG8_SA(b, h) + aoff + m * 2048 + k * 1024); } while (0)
; #define PG8_MMA(ai, bj, At, Bt) do { __builtin_amdgcn_s_setprio(1); _Pragma("unroll") for (int m = 0; m < 4; ++m) _Pragma("unroll") for (int n = 0; n < 2; ++n) _Pragma("unroll") for (int k = 0; k < 2; ++k) \
;         acc[ai][bj][m][n] = __builtin_amdgcn_mfma_f32_16x16x32_bf16(Bt[n][k], At[m][k], acc[ai][bj][m][n], 0, 0, 0); __builtin_amdgcn_s_setprio(0); } while (0)
; #define PG8_WAIT_V(n) asm volatile("s_waitcnt vmcnt(" #n ")" ::: "memory")
; #define PG8_WAIT_L(n) asm volatile("s_waitcnt lgkmcnt(" #n ")" ::: "memory")
; #define PG8_BAR __builtin_amdgcn_s_barrier()
; #define PG8_SCHED __builtin_amdgcn_sched_barrier(0)
; template <class Epi, class Sched, bool ALIGN_EPI = false, bool SP2 = false>
; __device__ __forceinline__ void gemm_phase(LAS unsigned char* lds, const Gemm g, const Sched& S, const Epi& E) {
;     ...
;             PG8_LDA(At, 1, 1); PG8_STAGE(PG8_SB(1, 0), b3, voffB); PG8_STAGE(PG8_SB(1, 1), b3 + hstep, voffB); PG8_STAGE(PG8_SA(1, 0), a3, voffA);
;             PG8_WAIT_V(8); PG8_WAIT_L(0); PG8_BAR; PG8_MMA(1, 0, At, B0); PG8_MMA(1, 1, At, B1); PG8_BAR; PG8_SCHED;
	s_add_i32 s30, s41, s9
	v_lshl_add_u64 v[210:211], v[210:211], 0, s[12:13]
	s_mov_b32 m0, s30
	ds_read_b128 v[178:181], v161 offset:49152
	ds_read_b128 v[182:185], v161 offset:50176
	ds_read_b128 v[186:189], v161 offset:51200
	ds_read_b128 v[190:193], v161 offset:52224
	ds_read_b128 v[194:197], v161 offset:53248
	ds_read_b128 v[198:201], v161 offset:54272
	ds_read_b128 v[202:205], v161 offset:55296
	ds_read_b128 v[206:209], v161 offset:56320
	global_load_lds_dwordx4 v[210:211], off
	s_add_i32 m0, s30, 0x2000
	s_add_u32 s28, s28, 0x80080
	v_lshl_add_u64 v[210:211], v[212:213], 0, s[12:13]
	s_addc_u32 s29, s29, 0
	s_add_i32 s30, s57, s9
	global_load_lds_dwordx4 v[210:211], off
	v_lshl_add_u64 v[210:211], s[28:29], 0, v[134:135]
	s_mov_b32 m0, s30
	s_nop 0
	global_load_lds_dwordx4 v[210:211], off
	v_lshl_add_u64 v[210:211], s[28:29], 0, v[130:131]
	s_add_i32 m0, s30, 0x2000
	s_nop 0
	global_load_lds_dwordx4 v[210:211], off
	v_lshl_add_u64 v[210:211], v[214:215], 0, s[12:13]
	s_mov_b32 m0, s53
	s_nop 0
	global_load_lds_dwordx4 v[210:211], off
	v_lshl_add_u64 v[210:211], v[216:217], 0, s[12:13]
	s_mov_b32 m0, s54
	s_nop 0
	global_load_lds_dwordx4 v[210:211], off
	s_waitcnt vmcnt(8)
	s_waitcnt lgkmcnt(0)
	s_barrier
	s_setprio 1
	s_waitcnt lgkmcnt(0)
	v_mfma_f32_16x16x32_bf16 v[62:65], v[142:145], v[178:181], v[62:65]
	v_mfma_f32_16x16x32_bf16 v[62:65], v[146:149], v[182:185], v[62:65]
	v_mfma_f32_16x16x32_bf16 v[58:61], v[150:153], v[178:181], v[58:61]
	v_mfma_f32_16x16x32_bf16 v[58:61], v[154:157], v[182:185], v[58:61]
	v_mfma_f32_16x16x32_bf16 v[42:45], v[150:153], v[186:189], v[42:45]
	v_mfma_f32_16x16x32_bf16 v[42:45], v[154:157], v[190:193], v[42:45]
	v_mfma_f32_16x16x32_bf16 v[46:49], v[142:145], v[186:189], v[46:49]
	v_mfma_f32_16x16x32_bf16 v[46:49], v[146:149], v[190:193], v[46:49]
	v_mfma_f32_16x16x32_bf16 v[30:33], v[142:145], v[194:197], v[30:33]
	v_mfma_f32_16x16x32_bf16 v[30:33], v[146:149], v[198:201], v[30:33]
	v_mfma_f32_16x16x32_bf16 v[26:29], v[150:153], v[194:197], v[26:29]
	v_mfma_f32_16x16x32_bf16 v[26:29], v[154:157], v[198:201], v[26:29]
	v_mfma_f32_16x16x32_bf16 v[10:13], v[150:153], v[202:205], v[10:13]
	v_mfma_f32_16x16x32_bf16 v[10:13], v[154:157], v[206:209], v[10:13]
	v_mfma_f32_16x16x32_bf16 v[14:17], v[142:145], v[202:205], v[14:17]
	v_mfma_f32_16x16x32_bf16 v[14:17], v[146:149], v[206:209], v[14:17]
	s_setprio 0
	s_setprio 1
	v_mfma_f32_16x16x32_bf16 v[54:57], v[162:165], v[178:181], v[54:57]
	v_mfma_f32_16x16x32_bf16 v[54:57], v[166:169], v[182:185], v[54:57]
	v_mfma_f32_16x16x32_bf16 v[50:53], v[170:173], v[178:181], v[50:53]
	v_mfma_f32_16x16x32_bf16 v[50:53], v[174:177], v[182:185], v[50:53]
	v_mfma_f32_16x16x32_bf16 v[34:37], v[170:173], v[186:189], v[34:37]
	v_mfma_f32_16x16x32_bf16 v[34:37], v[174:177], v[190:193], v[34:37]
	v_mfma_f32_16x16x32_bf16 v[38:41], v[162:165], v[186:189], v[38:41]
	v_mfma_f32_16x16x32_bf16 v[38:41], v[166:169], v[190:193], v[38:41]
	v_mfma_f32_16x16x32_bf16 v[22:25], v[162:165], v[194:197], v[22:25]
	v_mfma_f32_16x16x32_bf16 v[22:25], v[166:169], v[198:201], v[22:25]
	v_mfma_f32_16x16x32_bf16 v[18:21], v[170:173], v[194:197], v[18:21]
	v_mfma_f32_16x16x32_bf16 v[18:21], v[174:177], v[198:201], v[18:21]
	v_mfma_f32_16x16x32_bf16 v[2:5], v[170:173], v[202:205], v[2:5]
	v_mfma_f32_16x16x32_bf16 v[2:5], v[174:177], v[206:209], v[2:5]
	v_mfma_f32_16x16x32_bf16 v[6:9], v[162:165], v[202:205], v[6:9]
	v_mfma_f32_16x16x32_bf16 v[6:9], v[166:169], v[206:209], v[6:9]
	s_setprio 0
	s_barrier
	s_add_i32 s40, s40, 2
	s_add_u32 s26, s26, 0x100
	s_addc_u32 s27, s27, 0
	s_add_u32 s21, s21, 0x100
	s_addc_u32 s35, s35, 0
	s_cmp_gt_u32 s40, 29
	s_cbranch_scc0 .LBB0_359
	s_and_b64 vcc, exec, s[16:17]
	s_cbranch_vccz .LBB0_362
	s_barrier

; #define PG8_STAGE(bufoff, gbase, voff) do { _Pragma("unroll") for (int _i = 0; _i < 2; ++_i) \
;         __builtin_amdgcn_global_load_lds((const unsigned*)((const char*)(gbase) + (voff)[_i]), (LAS unsigned*)(lds + (bufoff) + ldsw + _i * 8192), 16, 0, 0); } while (0)
; #define PG8_LDA(dst, b, h) do { _Pragma("unroll") for (int m = 0; m < 4; ++m) _Pragma("unroll") for (int k = 0; k < 2; ++k) dst[m][k] = *(const LAS bf16x8*)(lds + PG8_SA(b, h) + aoff + m * 2048 + k * 1024); } while (0)
; #define PG8_LDB(dst, b, h) do { _Pragma("unroll") for (int n = 0; n < 2; ++n) _Pragma("unroll") for (int k = 0; k < 2; ++k) dst[n][k] = *(const LAS bf16x8*)(lds + PG8_SB(b, h) + boff + n * 2048 + k * 1024); } while (0)
; #define PG8_WAIT_V(n) asm volatile("s_waitcnt vmcnt(" #n ")" ::: "memory")
; #define PG8_WAIT_L(n) asm volatile("s_waitcnt lgkmcnt(" #n ")" ::: "memory")
; #define PG8_BAR __builtin_amdgcn_s_barrier()
; #define PG8_SCHED __builtin_amdgcn_sched_barrier(0)
; template <class Epi, class Sched, bool ALIGN_EPI = false, bool SP2 = false>
; __device__ __forceinline__ void gemm_phase(LAS unsigned char* lds, const Gemm g, const Sched& S, const Epi& E) {
;     ...
;         const bool has_next = S.next(ui + 1, nxt);
;         const char* nA = has_next ? (const char*)g.A + (size_t)nxt.pm * tstep : cA; const char* nB = has_next ? (const char*)g.Bt + (size_t)nxt.pn * tstep : cB;
;         for (int t = 0; t < nt; t += 2) {
;             const bool last = (t == nt - 2);
;             const char* a1 = cA + (size_t)(t + 1) * kstep;
;             const char* a2 = last ? nA : cA + (size_t)(t + 2) * kstep; const char* b2 = last ? nB : cB + (size_t)(t + 2) * kstep;
;             const char* a3 = a2 + kstep; const char* b3 = b2 + kstep;
;             if (last && has_next) S.a_ready(nxt);
;             if constexpr (SP2) {
;             PG8_LDB(B0, 0, 0); PG8_LDB(B1, 0, 1); PG8_SCHED; PG8_LDA(At, 0, 0); PG8_STAGE(PG8_SA(1, 1), a1 + hstep, voffA);
;             PG8_WAIT_V(8); PG8_WAIT_L(0); PG8_BAR; PG8_MMA(0, 0, At, B0); PG8_MMA(0, 1, At, B1); PG8_BAR; PG8_SCHED;
;             PG8_LDA(At, 0, 1); PG8_STAGE(PG8_SB(0, 0), b2, voffB); PG8_STAGE(PG8_SB(0, 1), b2 + hstep, voffB); PG8_STAGE(PG8_SA(0, 0), a2, voffA);
;             PG8_WAIT_V(8); PG8_WAIT_L(0); PG8_BAR; PG8_MMA(1, 0, At, B0); PG8_MMA(1, 1, At, B1); PG8_BAR; PG8_SCHED;
.LBB0_833:
	s_add_u32 s28, s26, 0xfff80080
	s_addc_u32 s29, s27, -1
	s_add_i32 s53, 0, 0x10000
	s_cmp_eq_u32 s52, 28
	s_cselect_b32 s31, s21, s29
	s_cselect_b32 s30, s48, s28
	s_cselect_b32 s29, s19, s51
	s_cselect_b32 s28, s49, s50
	s_add_i32 s56, 0, 0x14000
	v_add_u32_e32 v134, s53, v247
	v_add_u32_e32 v158, s56, v247
	ds_read_b128 v[106:109], v134
	ds_read_b128 v[110:113], v134 offset:1024
	ds_read_b128 v[122:125], v134 offset:2048
	ds_read_b128 v[134:137], v134 offset:3072
	ds_read_b128 v[146:149], v158
	ds_read_b128 v[150:153], v158 offset:1024
	ds_read_b128 v[154:157], v158 offset:2048
	ds_read_b128 v[158:161], v158 offset:3072
	v_lshl_add_u64 v[204:205], s[26:27], 0, v[200:201]
	s_add_i32 m0, s8, 0xc000
	ds_read_b128 v[162:165], v249
	ds_read_b128 v[166:169], v249 offset:1024
	ds_read_b128 v[170:173], v249 offset:2048
	ds_read_b128 v[174:177], v249 offset:3072
	ds_read_b128 v[178:181], v249 offset:4096
	ds_read_b128 v[182:185], v249 offset:5120
	ds_read_b128 v[186:189], v249 offset:6144
	ds_read_b128 v[190:193], v249 offset:7168
	global_load_lds_dwordx4 v[204:205], off
	v_lshl_add_u64 v[204:205], s[26:27], 0, v[202:203]
	s_add_i32 m0, s8, 0xe000
	s_nop 0
	global_load_lds_dwordx4 v[204:205], off
	s_waitcnt vmcnt(8)
	s_waitcnt lgkmcnt(0)
	s_barrier
	s_setprio 1
	s_waitcnt lgkmcnt(0)
	v_mfma_f32_16x16x32_bf16 v[142:145], v[106:109], v[162:165], v[142:145]
	v_mfma_f32_16x16x32_bf16 v[142:145], v[110:113], v[166:169], v[142:145]
	v_mfma_f32_16x16x32_bf16 v[138:141], v[122:125], v[162:165], v[138:141]
	v_mfma_f32_16x16x32_bf16 v[138:141], v[134:137], v[166:169], v[138:141]
	v_mfma_f32_16x16x32_bf16 v[114:117], v[122:125], v[170:173], v[114:117]
	v_mfma_f32_16x16x32_bf16 v[114:117], v[134:137], v[174:177], v[114:117]
	v_mfma_f32_16x16x32_bf16 v[118:121], v[106:109], v[170:173], v[118:121]
	v_mfma_f32_16x16x32_bf16 v[118:121], v[110:113], v[174:177], v[118:121]
	v_mfma_f32_16x16x32_bf16 v[94:97], v[106:109], v[178:181], v[94:97]
	v_mfma_f32_16x16x32_bf16 v[94:97], v[110:113], v[182:185], v[94:97]
	v_mfma_f32_16x16x32_bf16 v[90:93], v[122:125], v[178:181], v[90:93]
	v_mfma_f32_16x16x32_bf16 v[90:93], v[134:137], v[182:185], v[90:93]
	v_mfma_f32_16x16x32_bf16 v[74:77], v[122:125], v[186:189], v[74:77]
	v_mfma_f32_16x16x32_bf16 v[74:77], v[134:137], v[190:193], v[74:77]
	v_mfma_f32_16x16x32_bf16 v[78:81], v[106:109], v[186:189], v[78:81]
	v_mfma_f32_16x16x32_bf16 v[78:81], v[110:113], v[190:193], v[78:81]
	s_setprio 0
	s_setprio 1
	v_mfma_f32_16x16x32_bf16 v[130:133], v[146:149], v[162:165], v[130:133]
	v_mfma_f32_16x16x32_bf16 v[130:133], v[150:153], v[166:169], v[130:133]
	v_mfma_f32_16x16x32_bf16 v[126:129], v[154:157], v[162:165], v[126:129]
	v_mfma_f32_16x16x32_bf16 v[126:129], v[158:161], v[166:169], v[126:129]
	v_mfma_f32_16x16x32_bf16 v[98:101], v[154:157], v[170:173], v[98:101]
	v_mfma_f32_16x16x32_bf16 v[98:101], v[158:161], v[174:177], v[98:101]
	v_mfma_f32_16x16x32_bf16 v[102:105], v[146:149], v[170:173], v[102:105]
	v_mfma_f32_16x16x32_bf16 v[102:105], v[150:153], v[174:177], v[102:105]
	v_mfma_f32_16x16x32_bf16 v[86:89], v[146:149], v[178:181], v[86:89]
	v_mfma_f32_16x16x32_bf16 v[86:89], v[150:153], v[182:185], v[86:89]
	v_mfma_f32_16x16x32_bf16 v[82:85], v[154:157], v[178:181], v[82:85]
	v_mfma_f32_16x16x32_bf16 v[82:85], v[158:161], v[182:185], v[82:85]
	v_mfma_f32_16x16x32_bf16 v[66:69], v[154:157], v[186:189], v[66:69]
	v_mfma_f32_16x16x32_bf16 v[66:69], v[158:161], v[190:193], v[66:69]
	v_mfma_f32_16x16x32_bf16 v[70:73], v[146:149], v[186:189], v[70:73]
	v_mfma_f32_16x16x32_bf16 v[70:73], v[150:153], v[190:193], v[70:73]
	s_setprio 0
	s_barrier
	s_add_i32 s53, s53, s7
	v_lshl_add_u64 v[204:205], s[28:29], 0, v[0:1]
	s_mov_b32 m0, s53
	ds_read_b128 v[162:165], v249 offset:16384
	ds_read_b128 v[166:169], v249 offset:17408
	ds_read_b128 v[170:173], v249 offset:18432
	ds_read_b128 v[174:177], v249 offset:19456
	ds_read_b128 v[178:181], v249 offset:20480
	ds_read_b128 v[182:185], v249 offset:21504
	ds_read_b128 v[186:189], v249 offset:22528
	ds_read_b128 v[190:193], v249 offset:23552
	global_load_lds_dwordx4 v[204:205], off
	s_add_i32 m0, s53, 0x2000
	s_add_u32 s54, s28, 0x80000
	v_lshl_add_u64 v[206:207], s[28:29], 0, v[194:195]
	s_addc_u32 s55, s29, 0
	s_add_i32 s53, s56, s7
	global_load_lds_dwordx4 v[206:207], off
	v_lshl_add_u64 v[208:209], s[54:55], 0, v[0:1]
	s_mov_b32 m0, s53
	v_lshl_add_u64 v[210:211], s[30:31], 0, v[196:197]
	global_load_lds_dwordx4 v[208:209], off
	v_lshl_add_u64 v[208:209], s[54:55], 0, v[194:195]
	s_add_i32 m0, s53, 0x2000
	s_nop 0
	global_load_lds_dwordx4 v[208:209], off
	v_lshl_add_u64 v[208:209], s[30:31], 0, v[198:199]
	s_mov_b32 m0, s8
	s_nop 0
	global_load_lds_dwordx4 v[208:209], off
	s_mov_b32 m0, s9
	s_nop 0
	global_load_lds_dwordx4 v[210:211], off
	s_waitcnt vmcnt(8)
	s_waitcnt lgkmcnt(0)
	s_barrier
; #define PG8_STAGE(bufoff, gbase, voff) do { _Pragma("unroll") for (int _i = 0; _i < 2; ++_i) \
;         __builtin_amdgcn_global_load_lds((const unsigned*)((const char*)(gbase) + (voff)[_i]), (LAS unsigned*)(lds + (bufoff) + ldsw + _i * 8192), 16, 0, 0); } while (0)
; #define PG8_LDA(dst, b, h) do { _Pragma("unroll") for (int m = 0; m < 4; ++m) _Pragma("unroll") for (int k = 0; k < 2; ++k) dst[m][k] = *(const LAS bf16x8*)(lds + PG8_SA(b, h) + aoff + m * 2048 + k * 1024); } while (0)
; #define PG8_LDB(dst, b, h) do { _Pragma("unroll") for (int n = 0; n < 2; ++n) _Pragma("unroll") for (int k = 0; k < 2; ++k) dst[n][k] = *(const LAS bf16x8*)(lds + PG8_SB(b, h) + boff + n * 2048 + k * 1024); } while (0)
; #define PG8_MMA(ai, bj, At, Bt) do { __builtin_amdgcn_s_setprio(1); _Pragma("unroll") for (int m = 0; m < 4; ++m) _Pragma("unroll") for (int n = 0; n < 2; ++n) _Pragma("unroll") for (int k = 0; k < 2; ++k) \
;         acc[ai][bj][m][n] = __builtin_amdgcn_mfma_f32_16x16x32_bf16(Bt[n][k], At[m][k], acc[ai][bj][m][n], 0, 0, 0); __builtin_amdgcn_s_setprio(0); } while (0)
; #define PG8_WAIT_V(n) asm volatile("s_waitcnt vmcnt(" #n ")" ::: "memory")
; #define PG8_WAIT_L(n) asm volatile("s_waitcnt lgkmcnt(" #n ")" ::: "memory")
; #define PG8_BAR __builtin_amdgcn_s_barrier()
; #define PG8_SCHED __builtin_amdgcn_sched_barrier(0)
; template <class Epi, class Sched, bool ALIGN_EPI = false, bool SP2 = false>
; __device__ __forceinline__ void gemm_phase(LAS unsigned char* lds, const Gemm g, const Sched& S, const Epi& E) {
;     ...
;             PG8_WAIT_V(8); PG8_WAIT_L(0); PG8_BAR; PG8_MMA(1, 0, At, B0); PG8_MMA(1, 1, At, B1); PG8_BAR; PG8_SCHED;
;             PG8_LDB(B0, 1, 0); PG8_LDB(B1, 1, 1); PG8_SCHED; PG8_LDA(At, 1, 0); PG8_STAGE(PG8_SA(0, 1), a2 + hstep, voffA);
;             PG8_WAIT_V(8); PG8_WAIT_L(0); PG8_BAR; PG8_MMA(0, 0, At, B0); PG8_MMA(0, 1, At, B1); PG8_BAR; PG8_SCHED;
	s_setprio 1
	s_waitcnt lgkmcnt(0)
	v_mfma_f32_16x16x32_bf16 v[62:65], v[106:109], v[162:165], v[62:65]
	v_mfma_f32_16x16x32_bf16 v[62:65], v[110:113], v[166:169], v[62:65]
	v_mfma_f32_16x16x32_bf16 v[58:61], v[122:125], v[162:165], v[58:61]
	v_mfma_f32_16x16x32_bf16 v[58:61], v[134:137], v[166:169], v[58:61]
	v_mfma_f32_16x16x32_bf16 v[42:45], v[122:125], v[170:173], v[42:45]
	v_mfma_f32_16x16x32_bf16 v[42:45], v[134:137], v[174:177], v[42:45]
	v_mfma_f32_16x16x32_bf16 v[46:49], v[106:109], v[170:173], v[46:49]
	v_mfma_f32_16x16x32_bf16 v[46:49], v[110:113], v[174:177], v[46:49]
	v_mfma_f32_16x16x32_bf16 v[30:33], v[106:109], v[178:181], v[30:33]
	v_mfma_f32_16x16x32_bf16 v[30:33], v[110:113], v[182:185], v[30:33]
	v_mfma_f32_16x16x32_bf16 v[26:29], v[122:125], v[178:181], v[26:29]
	v_mfma_f32_16x16x32_bf16 v[26:29], v[134:137], v[182:185], v[26:29]
	v_mfma_f32_16x16x32_bf16 v[10:13], v[122:125], v[186:189], v[10:13]
	v_mfma_f32_16x16x32_bf16 v[10:13], v[134:137], v[190:193], v[10:13]
	v_mfma_f32_16x16x32_bf16 v[14:17], v[106:109], v[186:189], v[14:17]
	v_mfma_f32_16x16x32_bf16 v[14:17], v[110:113], v[190:193], v[14:17]
	s_setprio 0
	s_setprio 1
	v_mfma_f32_16x16x32_bf16 v[54:57], v[146:149], v[162:165], v[54:57]
	v_mfma_f32_16x16x32_bf16 v[54:57], v[150:153], v[166:169], v[54:57]
	v_mfma_f32_16x16x32_bf16 v[50:53], v[154:157], v[162:165], v[50:53]
	v_mfma_f32_16x16x32_bf16 v[50:53], v[158:161], v[166:169], v[50:53]
	v_mfma_f32_16x16x32_bf16 v[34:37], v[154:157], v[170:173], v[34:37]
	v_mfma_f32_16x16x32_bf16 v[34:37], v[158:161], v[174:177], v[34:37]
	v_mfma_f32_16x16x32_bf16 v[38:41], v[146:149], v[170:173], v[38:41]
	v_mfma_f32_16x16x32_bf16 v[38:41], v[150:153], v[174:177], v[38:41]
	v_mfma_f32_16x16x32_bf16 v[22:25], v[146:149], v[178:181], v[22:25]
	v_mfma_f32_16x16x32_bf16 v[22:25], v[150:153], v[182:185], v[22:25]
	v_mfma_f32_16x16x32_bf16 v[18:21], v[154:157], v[178:181], v[18:21]
	v_mfma_f32_16x16x32_bf16 v[18:21], v[158:161], v[182:185], v[18:21]
	v_mfma_f32_16x16x32_bf16 v[2:5], v[154:157], v[186:189], v[2:5]
	v_mfma_f32_16x16x32_bf16 v[2:5], v[158:161], v[190:193], v[2:5]
	v_mfma_f32_16x16x32_bf16 v[6:9], v[146:149], v[186:189], v[6:9]
	v_mfma_f32_16x16x32_bf16 v[6:9], v[150:153], v[190:193], v[6:9]
	s_setprio 0
	s_barrier
	s_add_i32 s53, 0, 0x18000
	s_add_i32 s54, 0, 0x1c000
	v_add_u32_e32 v134, s53, v247
	v_add_u32_e32 v158, s54, v247
	ds_read_b128 v[106:109], v134
	ds_read_b128 v[110:113], v134 offset:1024
	ds_read_b128 v[122:125], v134 offset:2048
	ds_read_b128 v[134:137], v134 offset:3072
	ds_read_b128 v[146:149], v158
	ds_read_b128 v[150:153], v158 offset:1024
	ds_read_b128 v[154:157], v158 offset:2048
	ds_read_b128 v[158:161], v158 offset:3072
	s_add_u32 s30, s30, 0x80000
	s_addc_u32 s31, s31, 0
	s_mov_b32 m0, s35
	v_lshl_add_u64 v[212:213], s[30:31], 0, v[198:199]
	ds_read_b128 v[162:165], v249 offset:32768
	ds_read_b128 v[166:169], v249 offset:33792
	ds_read_b128 v[170:173], v249 offset:34816
	ds_read_b128 v[174:177], v249 offset:35840
	ds_read_b128 v[178:181], v249 offset:36864
	ds_read_b128 v[182:185], v249 offset:37888
	ds_read_b128 v[186:189], v249 offset:38912
	ds_read_b128 v[190:193], v249 offset:39936
	global_load_lds_dwordx4 v[212:213], off
	v_lshl_add_u64 v[212:213], s[30:31], 0, v[196:197]
	s_mov_b32 m0, s42
	s_nop 0
	global_load_lds_dwordx4 v[212:213], off
	s_waitcnt vmcnt(8)
	s_waitcnt lgkmcnt(0)
	s_barrier
	s_setprio 1
	s_waitcnt lgkmcnt(0)
	v_mfma_f32_16x16x32_bf16 v[142:145], v[106:109], v[162:165], v[142:145]
	v_mfma_f32_16x16x32_bf16 v[142:145], v[110:113], v[166:169], v[142:145]
	v_mfma_f32_16x16x32_bf16 v[138:141], v[122:125], v[162:165], v[138:141]
	v_mfma_f32_16x16x32_bf16 v[138:141], v[134:137], v[166:169], v[138:141]
	v_mfma_f32_16x16x32_bf16 v[114:117], v[122:125], v[170:173], v[114:117]
	v_mfma_f32_16x16x32_bf16 v[114:117], v[134:137], v[174:177], v[114:117]
	v_mfma_f32_16x16x32_bf16 v[118:121], v[106:109], v[170:173], v[118:121]
	v_mfma_f32_16x16x32_bf16 v[118:121], v[110:113], v[174:177], v[118:121]
	v_mfma_f32_16x16x32_bf16 v[94:97], v[106:109], v[178:181], v[94:97]
	v_mfma_f32_16x16x32_bf16 v[94:97], v[110:113], v[182:185], v[94:97]
	v_mfma_f32_16x16x32_bf16 v[90:93], v[122:125], v[178:181], v[90:93]
	v_mfma_f32_16x16x32_bf16 v[90:93], v[134:137], v[182:185], v[90:93]
	v_mfma_f32_16x16x32_bf16 v[74:77], v[122:125], v[186:189], v[74:77]
	v_mfma_f32_16x16x32_bf16 v[74:77], v[134:137], v[190:193], v[74:77]
	v_mfma_f32_16x16x32_bf16 v[78:81], v[106:109], v[186:189], v[78:81]
	v_mfma_f32_16x16x32_bf16 v[78:81], v[110:113], v[190:193], v[78:81]
	s_setprio 0
	s_setprio 1
	v_mfma_f32_16x16x32_bf16 v[130:133], v[146:149], v[162:165], v[130:133]
	v_mfma_f32_16x16x32_bf16 v[130:133], v[150:153], v[166:169], v[130:133]
	v_mfma_f32_16x16x32_bf16 v[126:129], v[154:157], v[162:165], v[126:129]
	v_mfma_f32_16x16x32_bf16 v[126:129], v[158:161], v[166:169], v[126:129]
	v_mfma_f32_16x16x32_bf16 v[98:101], v[154:157], v[170:173], v[98:101]
	v_mfma_f32_16x16x32_bf16 v[98:101], v[158:161], v[174:177], v[98:101]
	v_mfma_f32_16x16x32_bf16 v[102:105], v[146:149], v[170:173], v[102:105]
	v_mfma_f32_16x16x32_bf16 v[102:105], v[150:153], v[174:177], v[102:105]
	v_mfma_f32_16x16x32_bf16 v[86:89], v[146:149], v[178:181], v[86:89]
	v_mfma_f32_16x16x32_bf16 v[86:89], v[150:153], v[182:185], v[86:89]
	v_mfma_f32_16x16x32_bf16 v[82:85], v[154:157], v[178:181], v[82:85]
	v_mfma_f32_16x16x32_bf16 v[82:85], v[158:161], v[182:185], v[82:85]
	v_mfma_f32_16x16x32_bf16 v[66:69], v[154:157], v[186:189], v[66:69]
	v_mfma_f32_16x16x32_bf16 v[66:69], v[158:161], v[190:193], v[66:69]
	v_mfma_f32_16x16x32_bf16 v[70:73], v[146:149], v[186:189], v[70:73]
	v_mfma_f32_16x16x32_bf16 v[70:73], v[150:153], v[190:193], v[70:73]
	s_setprio 0
	s_barrier
; #define PG8_STAGE(bufoff, gbase, voff) do { _Pragma("unroll") for (int _i = 0; _i < 2; ++_i) \
;         __builtin_amdgcn_global_load_lds((const unsigned*)((const char*)(gbase) + (voff)[_i]), (LAS unsigned*)(lds + (bufoff) + ldsw + _i * 8192), 16, 0, 0); } while (0)
; #define PG8_LDA(dst, b, h) do { _Pragma("unroll") for (int m = 0; m < 4; ++m) _Pragma("unroll") for (int k = 0; k < 2; ++k) dst[m][k] = *(const LAS bf16x8*)(lds + PG8_SA(b, h) + aoff + m * 2048 + k * 1024); } while (0)
; #define PG8_MMA(ai, bj, At, Bt) do { __builtin_amdgcn_s_setprio(1); _Pragma("unroll") for (int m = 0; m < 4; ++m) _Pragma("unroll") for (int n = 0; n < 2; ++n) _Pragma("unroll") for (int k = 0; k < 2; ++k) \
;         acc[ai][bj][m][n] = __builtin_amdgcn_mfma_f32_16x16x32_bf16(Bt[n][k], At[m][k], acc[ai][bj][m][n], 0, 0, 0); __builtin_amdgcn_s_setprio(0); } while (0)
; #define PG8_WAIT_V(n) asm volatile("s_waitcnt vmcnt(" #n ")" ::: "memory")
; #define PG8_WAIT_L(n) asm volatile("s_waitcnt lgkmcnt(" #n ")" ::: "memory")
; #define PG8_BAR __builtin_amdgcn_s_barrier()
; #define PG8_SCHED __builtin_amdgcn_sched_barrier(0)
; template <class Epi, class Sched, bool ALIGN_EPI = false, bool SP2 = false>
; __device__ __forceinline__ void gemm_phase(LAS unsigned char* lds, const Gemm g, const Sched& S, const Epi& E) {
;     ...
;             PG8_LDA(At, 1, 1); PG8_STAGE(PG8_SB(1, 0), b3, voffB); PG8_STAGE(PG8_SB(1, 1), b3 + hstep, voffB); PG8_STAGE(PG8_SA(1, 0), a3, voffA);
;             PG8_WAIT_V(8); PG8_WAIT_L(0); PG8_BAR; PG8_MMA(1, 0, At, B0); PG8_MMA(1, 1, At, B1); PG8_BAR; PG8_SCHED;
	s_add_i32 s30, s53, s7
	v_lshl_add_u64 v[204:205], v[204:205], 0, s[12:13]
	s_mov_b32 m0, s30
	ds_read_b128 v[162:165], v249 offset:49152
	ds_read_b128 v[166:169], v249 offset:50176
	ds_read_b128 v[170:173], v249 offset:51200
	ds_read_b128 v[174:177], v249 offset:52224
	ds_read_b128 v[178:181], v249 offset:53248
	ds_read_b128 v[182:185], v249 offset:54272
	ds_read_b128 v[186:189], v249 offset:55296
	ds_read_b128 v[190:193], v249 offset:56320
	global_load_lds_dwordx4 v[204:205], off
	s_add_i32 m0, s30, 0x2000
	s_add_u32 s28, s28, 0x80080
	v_lshl_add_u64 v[204:205], v[206:207], 0, s[12:13]
	s_addc_u32 s29, s29, 0
	s_add_i32 s30, s54, s7
	global_load_lds_dwordx4 v[204:205], off
	v_lshl_add_u64 v[204:205], s[28:29], 0, v[0:1]
	s_mov_b32 m0, s30
	s_nop 0
	global_load_lds_dwordx4 v[204:205], off
	v_lshl_add_u64 v[204:205], s[28:29], 0, v[194:195]
	s_add_i32 m0, s30, 0x2000
	s_nop 0
	global_load_lds_dwordx4 v[204:205], off
	v_lshl_add_u64 v[204:205], v[208:209], 0, s[12:13]
	s_mov_b32 m0, s43
	s_nop 0
	global_load_lds_dwordx4 v[204:205], off
	v_lshl_add_u64 v[204:205], v[210:211], 0, s[12:13]
	s_mov_b32 m0, s44
	s_nop 0
	global_load_lds_dwordx4 v[204:205], off
	s_waitcnt vmcnt(8)
	s_waitcnt lgkmcnt(0)
	s_barrier
	s_setprio 1
	s_waitcnt lgkmcnt(0)
	v_mfma_f32_16x16x32_bf16 v[62:65], v[106:109], v[162:165], v[62:65]
	v_mfma_f32_16x16x32_bf16 v[62:65], v[110:113], v[166:169], v[62:65]
	v_mfma_f32_16x16x32_bf16 v[58:61], v[122:125], v[162:165], v[58:61]
	v_mfma_f32_16x16x32_bf16 v[58:61], v[134:137], v[166:169], v[58:61]
	v_mfma_f32_16x16x32_bf16 v[42:45], v[122:125], v[170:173], v[42:45]
	v_mfma_f32_16x16x32_bf16 v[42:45], v[134:137], v[174:177], v[42:45]
	v_mfma_f32_16x16x32_bf16 v[46:49], v[106:109], v[170:173], v[46:49]
	v_mfma_f32_16x16x32_bf16 v[46:49], v[110:113], v[174:177], v[46:49]
	v_mfma_f32_16x16x32_bf16 v[30:33], v[106:109], v[178:181], v[30:33]
	v_mfma_f32_16x16x32_bf16 v[30:33], v[110:113], v[182:185], v[30:33]
	v_mfma_f32_16x16x32_bf16 v[26:29], v[122:125], v[178:181], v[26:29]
	v_mfma_f32_16x16x32_bf16 v[26:29], v[134:137], v[182:185], v[26:29]
	v_mfma_f32_16x16x32_bf16 v[10:13], v[122:125], v[186:189], v[10:13]
	v_mfma_f32_16x16x32_bf16 v[10:13], v[134:137], v[190:193], v[10:13]
	v_mfma_f32_16x16x32_bf16 v[14:17], v[106:109], v[186:189], v[14:17]
	v_mfma_f32_16x16x32_bf16 v[14:17], v[110:113], v[190:193], v[14:17]
	s_setprio 0
	s_setprio 1
	v_mfma_f32_16x16x32_bf16 v[54:57], v[146:149], v[162:165], v[54:57]
	v_mfma_f32_16x16x32_bf16 v[54:57], v[150:153], v[166:169], v[54:57]
	v_mfma_f32_16x16x32_bf16 v[50:53], v[154:157], v[162:165], v[50:53]
	v_mfma_f32_16x16x32_bf16 v[50:53], v[158:161], v[166:169], v[50:53]
	v_mfma_f32_16x16x32_bf16 v[34:37], v[154:157], v[170:173], v[34:37]
	v_mfma_f32_16x16x32_bf16 v[34:37], v[158:161], v[174:177], v[34:37]
	v_mfma_f32_16x16x32_bf16 v[38:41], v[146:149], v[170:173], v[38:41]
	v_mfma_f32_16x16x32_bf16 v[38:41], v[150:153], v[174:177], v[38:41]
	v_mfma_f32_16x16x32_bf16 v[22:25], v[146:149], v[178:181], v[22:25]
	v_mfma_f32_16x16x32_bf16 v[22:25], v[150:153], v[182:185], v[22:25]
	v_mfma_f32_16x16x32_bf16 v[18:21], v[154:157], v[178:181], v[18:21]
	v_mfma_f32_16x16x32_bf16 v[18:21], v[158:161], v[182:185], v[18:21]
	v_mfma_f32_16x16x32_bf16 v[2:5], v[154:157], v[186:189], v[2:5]
	v_mfma_f32_16x16x32_bf16 v[2:5], v[158:161], v[190:193], v[2:5]
	v_mfma_f32_16x16x32_bf16 v[6:9], v[146:149], v[186:189], v[6:9]
	v_mfma_f32_16x16x32_bf16 v[6:9], v[150:153], v[190:193], v[6:9]
	s_setprio 0
	s_barrier
	s_add_i32 s52, s52, 2
	s_add_u32 s26, s26, 0x100
	s_addc_u32 s27, s27, 0
	s_add_u32 s50, s50, 0x100
	s_addc_u32 s51, s51, 0
	s_cmp_gt_u32 s52, 29
	s_cbranch_scc0 .LBB0_833
	s_and_b64 vcc, exec, s[16:17]
	s_cbranch_vccz .LBB0_836
	s_barrier

; #define PG8_STAGE(bufoff, gbase, voff) do { _Pragma("unroll") for (int _i = 0; _i < 2; ++_i) \
;         __builtin_amdgcn_global_load_lds((const unsigned*)((const char*)(gbase) + (voff)[_i]), (LAS unsigned*)(lds + (bufoff) + ldsw + _i * 8192), 16, 0, 0); } while (0)
; #define PG8_LDA(dst, b, h) do { _Pragma("unroll") for (int m = 0; m < 4; ++m) _Pragma("unroll") for (int k = 0; k < 2; ++k) dst[m][k] = *(const LAS bf16x8*)(lds + PG8_SA(b, h) + aoff + m * 2048 + k * 1024); } while (0)
; #define PG8_LDB(dst, b, h) do { _Pragma("unroll") for (int n = 0; n < 2; ++n) _Pragma("unroll") for (int k = 0; k < 2; ++k) dst[n][k] = *(const LAS bf16x8*)(lds + PG8_SB(b, h) + boff + n * 2048 + k * 1024); } while (0)
; #define PG8_WAIT_V(n) asm volatile("s_waitcnt vmcnt(" #n ")" ::: "memory")
; #define PG8_WAIT_L(n) asm volatile("s_waitcnt lgkmcnt(" #n ")" ::: "memory")
; #define PG8_BAR __builtin_amdgcn_s_barrier()
; #define PG8_SCHED __builtin_amdgcn_sched_barrier(0)
; template <class Epi, class Sched, bool ALIGN_EPI = false, bool SP2 = false>
; __device__ __forceinline__ void gemm_phase(LAS unsigned char* lds, const Gemm g, const Sched& S, const Epi& E) {
;     ...
;         const bool has_next = S.next(ui + 1, nxt);
;         const char* nA = has_next ? (const char*)g.A + (size_t)nxt.pm * tstep : cA; const char* nB = has_next ? (const char*)g.Bt + (size_t)nxt.pn * tstep : cB;
;         for (int t = 0; t < nt; t += 2) {
;             const bool last = (t == nt - 2);
;             const char* a1 = cA + (size_t)(t + 1) * kstep;
;             const char* a2 = last ? nA : cA + (size_t)(t + 2) * kstep; const char* b2 = last ? nB : cB + (size_t)(t + 2) * kstep;
;             const char* a3 = a2 + kstep; const char* b3 = b2 + kstep;
;             if (last && has_next) S.a_ready(nxt);
;             if constexpr (SP2) {
;             PG8_LDB(B0, 0, 0); PG8_LDB(B1, 0, 1); PG8_SCHED; PG8_LDA(At, 0, 0); PG8_STAGE(PG8_SA(1, 1), a1 + hstep, voffA);
;             PG8_WAIT_V(8); PG8_WAIT_L(0); PG8_BAR; PG8_MMA(0, 0, At, B0); PG8_MMA(0, 1, At, B1); PG8_BAR; PG8_SCHED;
;             PG8_LDA(At, 0, 1); PG8_STAGE(PG8_SB(0, 0), b2, voffB); PG8_STAGE(PG8_SB(0, 1), b2 + hstep, voffB); PG8_STAGE(PG8_SA(0, 0), a2, voffA);
;             PG8_WAIT_V(8); PG8_WAIT_L(0); PG8_BAR; PG8_MMA(1, 0, At, B0); PG8_MMA(1, 1, At, B1); PG8_BAR; PG8_SCHED;
.LBB0_924:
	s_add_u32 s28, s26, 0xfff80080
	s_addc_u32 s29, s27, -1
	s_add_i32 s51, 0, 0x10000
	s_cmp_eq_u32 s50, 28
	s_cselect_b32 s31, s7, s29
	s_cselect_b32 s30, s8, s28
	v_add_u32_e32 v148, s51, v151
	s_cselect_b32 s29, s19, s49
	s_cselect_b32 s28, s21, s35
	s_add_i32 s54, 0, 0x14000
	ds_read_b128 v[140:143], v148
	ds_read_b128 v[144:147], v148 offset:1024
	ds_read_b128 v[156:159], v148 offset:2048
	ds_read_b128 v[160:163], v148 offset:3072
	v_add_u32_e32 v148, s54, v151
	ds_read_b128 v[164:167], v148
	ds_read_b128 v[168:171], v148 offset:1024
	ds_read_b128 v[172:175], v148 offset:2048
	ds_read_b128 v[176:179], v148 offset:3072
	v_lshl_add_u64 v[212:213], s[26:27], 0, v[136:137]
	s_add_i32 m0, s42, 0xc000
	ds_read_b128 v[180:183], v155
	ds_read_b128 v[184:187], v155 offset:1024
	ds_read_b128 v[188:191], v155 offset:2048
	ds_read_b128 v[192:195], v155 offset:3072
	ds_read_b128 v[196:199], v155 offset:4096
	ds_read_b128 v[200:203], v155 offset:5120
	ds_read_b128 v[204:207], v155 offset:6144
	ds_read_b128 v[208:211], v155 offset:7168
	global_load_lds_dwordx4 v[212:213], off
	v_lshl_add_u64 v[212:213], s[26:27], 0, v[138:139]
	s_add_i32 m0, s42, 0xe000
	s_nop 0
	global_load_lds_dwordx4 v[212:213], off
	s_waitcnt vmcnt(8)
	s_waitcnt lgkmcnt(0)
	s_barrier
	s_setprio 1
	s_waitcnt lgkmcnt(0)
	v_mfma_f32_16x16x32_bf16 v[126:129], v[140:143], v[180:183], v[126:129]
	v_mfma_f32_16x16x32_bf16 v[126:129], v[144:147], v[184:187], v[126:129]
	v_mfma_f32_16x16x32_bf16 v[122:125], v[156:159], v[180:183], v[122:125]
	v_mfma_f32_16x16x32_bf16 v[122:125], v[160:163], v[184:187], v[122:125]
	v_mfma_f32_16x16x32_bf16 v[106:109], v[156:159], v[188:191], v[106:109]
	v_mfma_f32_16x16x32_bf16 v[106:109], v[160:163], v[192:195], v[106:109]
	v_mfma_f32_16x16x32_bf16 v[110:113], v[140:143], v[188:191], v[110:113]
	v_mfma_f32_16x16x32_bf16 v[110:113], v[144:147], v[192:195], v[110:113]
	v_mfma_f32_16x16x32_bf16 v[94:97], v[140:143], v[196:199], v[94:97]
	v_mfma_f32_16x16x32_bf16 v[94:97], v[144:147], v[200:203], v[94:97]
	v_mfma_f32_16x16x32_bf16 v[90:93], v[156:159], v[196:199], v[90:93]
	v_mfma_f32_16x16x32_bf16 v[90:93], v[160:163], v[200:203], v[90:93]
	v_mfma_f32_16x16x32_bf16 v[74:77], v[156:159], v[204:207], v[74:77]
	v_mfma_f32_16x16x32_bf16 v[74:77], v[160:163], v[208:211], v[74:77]
	v_mfma_f32_16x16x32_bf16 v[78:81], v[140:143], v[204:207], v[78:81]
	v_mfma_f32_16x16x32_bf16 v[78:81], v[144:147], v[208:211], v[78:81]
	s_setprio 0
	s_setprio 1
	v_mfma_f32_16x16x32_bf16 v[118:121], v[164:167], v[180:183], v[118:121]
	v_mfma_f32_16x16x32_bf16 v[118:121], v[168:171], v[184:187], v[118:121]
	v_mfma_f32_16x16x32_bf16 v[114:117], v[172:175], v[180:183], v[114:117]
	v_mfma_f32_16x16x32_bf16 v[114:117], v[176:179], v[184:187], v[114:117]
	v_mfma_f32_16x16x32_bf16 v[98:101], v[172:175], v[188:191], v[98:101]
	v_mfma_f32_16x16x32_bf16 v[98:101], v[176:179], v[192:195], v[98:101]
	v_mfma_f32_16x16x32_bf16 v[102:105], v[164:167], v[188:191], v[102:105]
	v_mfma_f32_16x16x32_bf16 v[102:105], v[168:171], v[192:195], v[102:105]
	v_mfma_f32_16x16x32_bf16 v[86:89], v[164:167], v[196:199], v[86:89]
	v_mfma_f32_16x16x32_bf16 v[86:89], v[168:171], v[200:203], v[86:89]
	v_mfma_f32_16x16x32_bf16 v[82:85], v[172:175], v[196:199], v[82:85]
	v_mfma_f32_16x16x32_bf16 v[82:85], v[176:179], v[200:203], v[82:85]
	v_mfma_f32_16x16x32_bf16 v[66:69], v[172:175], v[204:207], v[66:69]
	v_mfma_f32_16x16x32_bf16 v[66:69], v[176:179], v[208:211], v[66:69]
	v_mfma_f32_16x16x32_bf16 v[70:73], v[164:167], v[204:207], v[70:73]
	v_mfma_f32_16x16x32_bf16 v[70:73], v[168:171], v[208:211], v[70:73]
	s_setprio 0
	s_barrier
	s_add_i32 s51, s51, s41
	v_lshl_add_u64 v[212:213], s[28:29], 0, v[0:1]
	s_mov_b32 m0, s51
	ds_read_b128 v[180:183], v155 offset:16384
	ds_read_b128 v[184:187], v155 offset:17408
	ds_read_b128 v[188:191], v155 offset:18432
	ds_read_b128 v[192:195], v155 offset:19456
	ds_read_b128 v[196:199], v155 offset:20480
	ds_read_b128 v[200:203], v155 offset:21504
	ds_read_b128 v[204:207], v155 offset:22528
	ds_read_b128 v[208:211], v155 offset:23552
	global_load_lds_dwordx4 v[212:213], off
	s_add_i32 m0, s51, 0x2000
	s_add_u32 s52, s28, 0x80000
	v_lshl_add_u64 v[214:215], s[28:29], 0, v[130:131]
	s_addc_u32 s53, s29, 0
	s_add_i32 s51, s54, s41
	global_load_lds_dwordx4 v[214:215], off
	v_lshl_add_u64 v[216:217], s[52:53], 0, v[0:1]
	s_mov_b32 m0, s51
	v_lshl_add_u64 v[218:219], s[30:31], 0, v[132:133]
	global_load_lds_dwordx4 v[216:217], off
	v_lshl_add_u64 v[216:217], s[52:53], 0, v[130:131]
	s_add_i32 m0, s51, 0x2000
	s_nop 0
	global_load_lds_dwordx4 v[216:217], off
	v_lshl_add_u64 v[216:217], s[30:31], 0, v[134:135]
	s_mov_b32 m0, s42
	s_nop 0
	global_load_lds_dwordx4 v[216:217], off
	s_mov_b32 m0, s43
	s_nop 0
	global_load_lds_dwordx4 v[218:219], off
	s_waitcnt vmcnt(8)
	s_waitcnt lgkmcnt(0)
	s_barrier
; #define PG8_STAGE(bufoff, gbase, voff) do { _Pragma("unroll") for (int _i = 0; _i < 2; ++_i) \
;         __builtin_amdgcn_global_load_lds((const unsigned*)((const char*)(gbase) + (voff)[_i]), (LAS unsigned*)(lds + (bufoff) + ldsw + _i * 8192), 16, 0, 0); } while (0)
; #define PG8_LDA(dst, b, h) do { _Pragma("unroll") for (int m = 0; m < 4; ++m) _Pragma("unroll") for (int k = 0; k < 2; ++k) dst[m][k] = *(const LAS bf16x8*)(lds + PG8_SA(b, h) + aoff + m * 2048 + k * 1024); } while (0)
; #define PG8_LDB(dst, b, h) do { _Pragma("unroll") for (int n = 0; n < 2; ++n) _Pragma("unroll") for (int k = 0; k < 2; ++k) dst[n][k] = *(const LAS bf16x8*)(lds + PG8_SB(b, h) + boff + n * 2048 + k * 1024); } while (0)
; #define PG8_MMA(ai, bj, At, Bt) do { __builtin_amdgcn_s_setprio(1); _Pragma("unroll") for (int m = 0; m < 4; ++m) _Pragma("unroll") for (int n = 0; n < 2; ++n) _Pragma("unroll") for (int k = 0; k < 2; ++k) \
;         acc[ai][bj][m][n] = __builtin_amdgcn_mfma_f32_16x16x32_bf16(Bt[n][k], At[m][k], acc[ai][bj][m][n], 0, 0, 0); __builtin_amdgcn_s_setprio(0); } while (0)
; #define PG8_WAIT_V(n) asm volatile("s_waitcnt vmcnt(" #n ")" ::: "memory")
; #define PG8_WAIT_L(n) asm volatile("s_waitcnt lgkmcnt(" #n ")" ::: "memory")
; #define PG8_BAR __builtin_amdgcn_s_barrier()
; #define PG8_SCHED __builtin_amdgcn_sched_barrier(0)
; template <class Epi, class Sched, bool ALIGN_EPI = false, bool SP2 = false>
; __device__ __forceinline__ void gemm_phase(LAS unsigned char* lds, const Gemm g, const Sched& S, const Epi& E) {
;     ...
;             PG8_WAIT_V(8); PG8_WAIT_L(0); PG8_BAR; PG8_MMA(1, 0, At, B0); PG8_MMA(1, 1, At, B1); PG8_BAR; PG8_SCHED;
;             PG8_LDB(B0, 1, 0); PG8_LDB(B1, 1, 1); PG8_SCHED; PG8_LDA(At, 1, 0); PG8_STAGE(PG8_SA(0, 1), a2 + hstep, voffA);
;             PG8_WAIT_V(8); PG8_WAIT_L(0); PG8_BAR; PG8_MMA(0, 0, At, B0); PG8_MMA(0, 1, At, B1); PG8_BAR; PG8_SCHED;
	s_setprio 1
	s_waitcnt lgkmcnt(0)
	v_mfma_f32_16x16x32_bf16 v[62:65], v[140:143], v[180:183], v[62:65]
	v_mfma_f32_16x16x32_bf16 v[62:65], v[144:147], v[184:187], v[62:65]
	v_mfma_f32_16x16x32_bf16 v[58:61], v[156:159], v[180:183], v[58:61]
	v_mfma_f32_16x16x32_bf16 v[58:61], v[160:163], v[184:187], v[58:61]
	v_mfma_f32_16x16x32_bf16 v[42:45], v[156:159], v[188:191], v[42:45]
	v_mfma_f32_16x16x32_bf16 v[42:45], v[160:163], v[192:195], v[42:45]
	v_mfma_f32_16x16x32_bf16 v[46:49], v[140:143], v[188:191], v[46:49]
	v_mfma_f32_16x16x32_bf16 v[46:49], v[144:147], v[192:195], v[46:49]
	v_mfma_f32_16x16x32_bf16 v[30:33], v[140:143], v[196:199], v[30:33]
	v_mfma_f32_16x16x32_bf16 v[30:33], v[144:147], v[200:203], v[30:33]
	v_mfma_f32_16x16x32_bf16 v[26:29], v[156:159], v[196:199], v[26:29]
	v_mfma_f32_16x16x32_bf16 v[26:29], v[160:163], v[200:203], v[26:29]
	v_mfma_f32_16x16x32_bf16 v[10:13], v[156:159], v[204:207], v[10:13]
	v_mfma_f32_16x16x32_bf16 v[10:13], v[160:163], v[208:211], v[10:13]
	v_mfma_f32_16x16x32_bf16 v[14:17], v[140:143], v[204:207], v[14:17]
	v_mfma_f32_16x16x32_bf16 v[14:17], v[144:147], v[208:211], v[14:17]
	s_setprio 0
	s_setprio 1
	v_mfma_f32_16x16x32_bf16 v[54:57], v[164:167], v[180:183], v[54:57]
	v_mfma_f32_16x16x32_bf16 v[54:57], v[168:171], v[184:187], v[54:57]
	v_mfma_f32_16x16x32_bf16 v[50:53], v[172:175], v[180:183], v[50:53]
	v_mfma_f32_16x16x32_bf16 v[50:53], v[176:179], v[184:187], v[50:53]
	v_mfma_f32_16x16x32_bf16 v[34:37], v[172:175], v[188:191], v[34:37]
	v_mfma_f32_16x16x32_bf16 v[34:37], v[176:179], v[192:195], v[34:37]
	v_mfma_f32_16x16x32_bf16 v[38:41], v[164:167], v[188:191], v[38:41]
	v_mfma_f32_16x16x32_bf16 v[38:41], v[168:171], v[192:195], v[38:41]
	v_mfma_f32_16x16x32_bf16 v[22:25], v[164:167], v[196:199], v[22:25]
	v_mfma_f32_16x16x32_bf16 v[22:25], v[168:171], v[200:203], v[22:25]
	v_mfma_f32_16x16x32_bf16 v[18:21], v[172:175], v[196:199], v[18:21]
	v_mfma_f32_16x16x32_bf16 v[18:21], v[176:179], v[200:203], v[18:21]
	v_mfma_f32_16x16x32_bf16 v[2:5], v[172:175], v[204:207], v[2:5]
	v_mfma_f32_16x16x32_bf16 v[2:5], v[176:179], v[208:211], v[2:5]
	v_mfma_f32_16x16x32_bf16 v[6:9], v[164:167], v[204:207], v[6:9]
	v_mfma_f32_16x16x32_bf16 v[6:9], v[168:171], v[208:211], v[6:9]
	s_setprio 0
	s_barrier
	s_add_i32 s51, 0, 0x18000
	v_add_u32_e32 v148, s51, v151
	s_add_i32 s52, 0, 0x1c000
	ds_read_b128 v[140:143], v148
	ds_read_b128 v[144:147], v148 offset:1024
	ds_read_b128 v[156:159], v148 offset:2048
	ds_read_b128 v[160:163], v148 offset:3072
	v_add_u32_e32 v148, s52, v151
	ds_read_b128 v[164:167], v148
	ds_read_b128 v[168:171], v148 offset:1024
	ds_read_b128 v[172:175], v148 offset:2048
	ds_read_b128 v[176:179], v148 offset:3072
	s_add_u32 s30, s30, 0x80000
	s_addc_u32 s31, s31, 0
	s_mov_b32 m0, s44
	v_lshl_add_u64 v[220:221], s[30:31], 0, v[134:135]
	ds_read_b128 v[180:183], v155 offset:32768
	ds_read_b128 v[184:187], v155 offset:33792
	ds_read_b128 v[188:191], v155 offset:34816
	ds_read_b128 v[192:195], v155 offset:35840
	ds_read_b128 v[196:199], v155 offset:36864
	ds_read_b128 v[200:203], v155 offset:37888
	ds_read_b128 v[204:207], v155 offset:38912
	ds_read_b128 v[208:211], v155 offset:39936
	global_load_lds_dwordx4 v[220:221], off
	v_lshl_add_u64 v[220:221], s[30:31], 0, v[132:133]
	s_mov_b32 m0, s45
	s_nop 0
	global_load_lds_dwordx4 v[220:221], off
	s_waitcnt vmcnt(8)
	s_waitcnt lgkmcnt(0)
	s_barrier
	s_setprio 1
	s_waitcnt lgkmcnt(0)
	v_mfma_f32_16x16x32_bf16 v[126:129], v[140:143], v[180:183], v[126:129]
	v_mfma_f32_16x16x32_bf16 v[126:129], v[144:147], v[184:187], v[126:129]
	v_mfma_f32_16x16x32_bf16 v[122:125], v[156:159], v[180:183], v[122:125]
	v_mfma_f32_16x16x32_bf16 v[122:125], v[160:163], v[184:187], v[122:125]
	v_mfma_f32_16x16x32_bf16 v[106:109], v[156:159], v[188:191], v[106:109]
	v_mfma_f32_16x16x32_bf16 v[106:109], v[160:163], v[192:195], v[106:109]
	v_mfma_f32_16x16x32_bf16 v[110:113], v[140:143], v[188:191], v[110:113]
	v_mfma_f32_16x16x32_bf16 v[110:113], v[144:147], v[192:195], v[110:113]
	v_mfma_f32_16x16x32_bf16 v[94:97], v[140:143], v[196:199], v[94:97]
	v_mfma_f32_16x16x32_bf16 v[94:97], v[144:147], v[200:203], v[94:97]
	v_mfma_f32_16x16x32_bf16 v[90:93], v[156:159], v[196:199], v[90:93]
	v_mfma_f32_16x16x32_bf16 v[90:93], v[160:163], v[200:203], v[90:93]
	v_mfma_f32_16x16x32_bf16 v[74:77], v[156:159], v[204:207], v[74:77]
	v_mfma_f32_16x16x32_bf16 v[74:77], v[160:163], v[208:211], v[74:77]
	v_mfma_f32_16x16x32_bf16 v[78:81], v[140:143], v[204:207], v[78:81]
	v_mfma_f32_16x16x32_bf16 v[78:81], v[144:147], v[208:211], v[78:81]
	s_setprio 0
	s_setprio 1
	v_mfma_f32_16x16x32_bf16 v[118:121], v[164:167], v[180:183], v[118:121]
	v_mfma_f32_16x16x32_bf16 v[118:121], v[168:171], v[184:187], v[118:121]
	v_mfma_f32_16x16x32_bf16 v[114:117], v[172:175], v[180:183], v[114:117]
	v_mfma_f32_16x16x32_bf16 v[114:117], v[176:179], v[184:187], v[114:117]
	v_mfma_f32_16x16x32_bf16 v[98:101], v[172:175], v[188:191], v[98:101]
	v_mfma_f32_16x16x32_bf16 v[98:101], v[176:179], v[192:195], v[98:101]
	v_mfma_f32_16x16x32_bf16 v[102:105], v[164:167], v[188:191], v[102:105]
	v_mfma_f32_16x16x32_bf16 v[102:105], v[168:171], v[192:195], v[102:105]
	v_mfma_f32_16x16x32_bf16 v[86:89], v[164:167], v[196:199], v[86:89]
	v_mfma_f32_16x16x32_bf16 v[86:89], v[168:171], v[200:203], v[86:89]
	v_mfma_f32_16x16x32_bf16 v[82:85], v[172:175], v[196:199], v[82:85]
	v_mfma_f32_16x16x32_bf16 v[82:85], v[176:179], v[200:203], v[82:85]
	v_mfma_f32_16x16x32_bf16 v[66:69], v[172:175], v[204:207], v[66:69]
	v_mfma_f32_16x16x32_bf16 v[66:69], v[176:179], v[208:211], v[66:69]
	v_mfma_f32_16x16x32_bf16 v[70:73], v[164:167], v[204:207], v[70:73]
	v_mfma_f32_16x16x32_bf16 v[70:73], v[168:171], v[208:211], v[70:73]
	s_setprio 0
	s_barrier
; #define PG8_STAGE(bufoff, gbase, voff) do { _Pragma("unroll") for (int _i = 0; _i < 2; ++_i) \
;         __builtin_amdgcn_global_load_lds((const unsigned*)((const char*)(gbase) + (voff)[_i]), (LAS unsigned*)(lds + (bufoff) + ldsw + _i * 8192), 16, 0, 0); } while (0)
; #define PG8_LDA(dst, b, h) do { _Pragma("unroll") for (int m = 0; m < 4; ++m) _Pragma("unroll") for (int k = 0; k < 2; ++k) dst[m][k] = *(const LAS bf16x8*)(lds + PG8_SA(b, h) + aoff + m * 2048 + k * 1024); } while (0)
; #define PG8_MMA(ai, bj, At, Bt) do { __builtin_amdgcn_s_setprio(1); _Pragma("unroll") for (int m = 0; m < 4; ++m) _Pragma("unroll") for (int n = 0; n < 2; ++n) _Pragma("unroll") for (int k = 0; k < 2; ++k) \
;         acc[ai][bj][m][n] = __builtin_amdgcn_mfma_f32_16x16x32_bf16(Bt[n][k], At[m][k], acc[ai][bj][m][n], 0, 0, 0); __builtin_amdgcn_s_setprio(0); } while (0)
; #define PG8_WAIT_V(n) asm volatile("s_waitcnt vmcnt(" #n ")" ::: "memory")
; #define PG8_WAIT_L(n) asm volatile("s_waitcnt lgkmcnt(" #n ")" ::: "memory")
; #define PG8_BAR __builtin_amdgcn_s_barrier()
; #define PG8_SCHED __builtin_amdgcn_sched_barrier(0)
; template <class Epi, class Sched, bool ALIGN_EPI = false, bool SP2 = false>
; __device__ __forceinline__ void gemm_phase(LAS unsigned char* lds, const Gemm g, const Sched& S, const Epi& E) {
;     ...
;             PG8_LDA(At, 1, 1); PG8_STAGE(PG8_SB(1, 0), b3, voffB); PG8_STAGE(PG8_SB(1, 1), b3 + hstep, voffB); PG8_STAGE(PG8_SA(1, 0), a3, voffA);
;             PG8_WAIT_V(8); PG8_WAIT_L(0); PG8_BAR; PG8_MMA(1, 0, At, B0); PG8_MMA(1, 1, At, B1); PG8_BAR; PG8_SCHED;
	s_add_i32 s30, s51, s41
	v_lshl_add_u64 v[212:213], v[212:213], 0, s[12:13]
	s_mov_b32 m0, s30
	ds_read_b128 v[180:183], v155 offset:49152
	ds_read_b128 v[184:187], v155 offset:50176
	ds_read_b128 v[188:191], v155 offset:51200
	ds_read_b128 v[192:195], v155 offset:52224
	ds_read_b128 v[196:199], v155 offset:53248
	ds_read_b128 v[200:203], v155 offset:54272
	ds_read_b128 v[204:207], v155 offset:55296
	ds_read_b128 v[208:211], v155 offset:56320
	global_load_lds_dwordx4 v[212:213], off
	s_add_i32 m0, s30, 0x2000
	s_add_u32 s28, s28, 0x80080
	v_lshl_add_u64 v[212:213], v[214:215], 0, s[12:13]
	s_addc_u32 s29, s29, 0
	s_add_i32 s30, s52, s41
	global_load_lds_dwordx4 v[212:213], off
	v_lshl_add_u64 v[212:213], s[28:29], 0, v[0:1]
	s_mov_b32 m0, s30
	s_nop 0
	global_load_lds_dwordx4 v[212:213], off
	v_lshl_add_u64 v[212:213], s[28:29], 0, v[130:131]
	s_add_i32 m0, s30, 0x2000
	s_nop 0
	global_load_lds_dwordx4 v[212:213], off
	v_lshl_add_u64 v[212:213], v[216:217], 0, s[12:13]
	s_mov_b32 m0, s46
	s_nop 0
	global_load_lds_dwordx4 v[212:213], off
	v_lshl_add_u64 v[212:213], v[218:219], 0, s[12:13]
	s_mov_b32 m0, s47
	s_nop 0
	global_load_lds_dwordx4 v[212:213], off
	s_waitcnt vmcnt(8)
	s_waitcnt lgkmcnt(0)
	s_barrier
	s_setprio 1
	s_waitcnt lgkmcnt(0)
	v_mfma_f32_16x16x32_bf16 v[62:65], v[140:143], v[180:183], v[62:65]
	v_mfma_f32_16x16x32_bf16 v[62:65], v[144:147], v[184:187], v[62:65]
	v_mfma_f32_16x16x32_bf16 v[58:61], v[156:159], v[180:183], v[58:61]
	v_mfma_f32_16x16x32_bf16 v[58:61], v[160:163], v[184:187], v[58:61]
	v_mfma_f32_16x16x32_bf16 v[42:45], v[156:159], v[188:191], v[42:45]
	v_mfma_f32_16x16x32_bf16 v[42:45], v[160:163], v[192:195], v[42:45]
	v_mfma_f32_16x16x32_bf16 v[46:49], v[140:143], v[188:191], v[46:49]
	v_mfma_f32_16x16x32_bf16 v[46:49], v[144:147], v[192:195], v[46:49]
	v_mfma_f32_16x16x32_bf16 v[30:33], v[140:143], v[196:199], v[30:33]
	v_mfma_f32_16x16x32_bf16 v[30:33], v[144:147], v[200:203], v[30:33]
	v_mfma_f32_16x16x32_bf16 v[26:29], v[156:159], v[196:199], v[26:29]
	v_mfma_f32_16x16x32_bf16 v[26:29], v[160:163], v[200:203], v[26:29]
	v_mfma_f32_16x16x32_bf16 v[10:13], v[156:159], v[204:207], v[10:13]
	v_mfma_f32_16x16x32_bf16 v[10:13], v[160:163], v[208:211], v[10:13]
	v_mfma_f32_16x16x32_bf16 v[14:17], v[140:143], v[204:207], v[14:17]
	v_mfma_f32_16x16x32_bf16 v[14:17], v[144:147], v[208:211], v[14:17]
	s_setprio 0
	s_setprio 1
	v_mfma_f32_16x16x32_bf16 v[54:57], v[164:167], v[180:183], v[54:57]
	v_mfma_f32_16x16x32_bf16 v[54:57], v[168:171], v[184:187], v[54:57]
	v_mfma_f32_16x16x32_bf16 v[50:53], v[172:175], v[180:183], v[50:53]
	v_mfma_f32_16x16x32_bf16 v[50:53], v[176:179], v[184:187], v[50:53]
	v_mfma_f32_16x16x32_bf16 v[34:37], v[172:175], v[188:191], v[34:37]
	v_mfma_f32_16x16x32_bf16 v[34:37], v[176:179], v[192:195], v[34:37]
	v_mfma_f32_16x16x32_bf16 v[38:41], v[164:167], v[188:191], v[38:41]
	v_mfma_f32_16x16x32_bf16 v[38:41], v[168:171], v[192:195], v[38:41]
	v_mfma_f32_16x16x32_bf16 v[22:25], v[164:167], v[196:199], v[22:25]
	v_mfma_f32_16x16x32_bf16 v[22:25], v[168:171], v[200:203], v[22:25]
	v_mfma_f32_16x16x32_bf16 v[18:21], v[172:175], v[196:199], v[18:21]
	v_mfma_f32_16x16x32_bf16 v[18:21], v[176:179], v[200:203], v[18:21]
	v_mfma_f32_16x16x32_bf16 v[2:5], v[172:175], v[204:207], v[2:5]
	v_mfma_f32_16x16x32_bf16 v[2:5], v[176:179], v[208:211], v[2:5]
	v_mfma_f32_16x16x32_bf16 v[6:9], v[164:167], v[204:207], v[6:9]
	v_mfma_f32_16x16x32_bf16 v[6:9], v[168:171], v[208:211], v[6:9]
	s_setprio 0
	s_barrier
	s_add_i32 s50, s50, 2
	s_add_u32 s26, s26, 0x100
	s_addc_u32 s27, s27, 0
	s_add_u32 s35, s35, 0x100
	s_addc_u32 s49, s49, 0
	s_cmp_gt_u32 s50, 29
	s_cbranch_scc0 .LBB0_924
	s_and_b64 vcc, exec, s[16:17]
	s_cbranch_vccz .LBB0_927
	s_barrier

; #define PG8_STAGE(bufoff, gbase, voff) do { _Pragma("unroll") for (int _i = 0; _i < 2; ++_i) \
;         __builtin_amdgcn_global_load_lds((const unsigned*)((const char*)(gbase) + (voff)[_i]), (LAS unsigned*)(lds + (bufoff) + ldsw + _i * 8192), 16, 0, 0); } while (0)
; #define PG8_LDA(dst, b, h) do { _Pragma("unroll") for (int m = 0; m < 4; ++m) _Pragma("unroll") for (int k = 0; k < 2; ++k) dst[m][k] = *(const LAS bf16x8*)(lds + PG8_SA(b, h) + aoff + m * 2048 + k * 1024); } while (0)
; #define PG8_LDB(dst, b, h) do { _Pragma("unroll") for (int n = 0; n < 2; ++n) _Pragma("unroll") for (int k = 0; k < 2; ++k) dst[n][k] = *(const LAS bf16x8*)(lds + PG8_SB(b, h) + boff + n * 2048 + k * 1024); } while (0)
; #define PG8_WAIT_V(n) asm volatile("s_waitcnt vmcnt(" #n ")" ::: "memory")
; #define PG8_WAIT_L(n) asm volatile("s_waitcnt lgkmcnt(" #n ")" ::: "memory")
; #define PG8_BAR __builtin_amdgcn_s_barrier()
; #define PG8_SCHED __builtin_amdgcn_sched_barrier(0)
; template <class Epi, class Sched, bool ALIGN_EPI = false, bool SP2 = false>
; __device__ __forceinline__ void gemm_phase(LAS unsigned char* lds, const Gemm g, const Sched& S, const Epi& E) {
;     ...
;         const bool has_next = S.next(ui + 1, nxt);
;         const char* nA = has_next ? (const char*)g.A + (size_t)nxt.pm * tstep : cA; const char* nB = has_next ? (const char*)g.Bt + (size_t)nxt.pn * tstep : cB;
;         for (int t = 0; t < nt; t += 2) {
;             const bool last = (t == nt - 2);
;             const char* a1 = cA + (size_t)(t + 1) * kstep;
;             const char* a2 = last ? nA : cA + (size_t)(t + 2) * kstep; const char* b2 = last ? nB : cB + (size_t)(t + 2) * kstep;
;             const char* a3 = a2 + kstep; const char* b3 = b2 + kstep;
;             if (last && has_next) S.a_ready(nxt);
;             if constexpr (SP2) {
;             PG8_LDB(B0, 0, 0); PG8_LDB(B1, 0, 1); PG8_SCHED; PG8_LDA(At, 0, 0); PG8_STAGE(PG8_SA(1, 1), a1 + hstep, voffA);
;             PG8_WAIT_V(8); PG8_WAIT_L(0); PG8_BAR; PG8_MMA(0, 0, At, B0); PG8_MMA(0, 1, At, B1); PG8_BAR; PG8_SCHED;
;             PG8_LDA(At, 0, 1); PG8_STAGE(PG8_SB(0, 0), b2, voffB); PG8_STAGE(PG8_SB(0, 1), b2 + hstep, voffB); PG8_STAGE(PG8_SA(0, 0), a2, voffA);
;             PG8_WAIT_V(8); PG8_WAIT_L(0); PG8_BAR; PG8_MMA(1, 0, At, B0); PG8_MMA(1, 1, At, B1); PG8_BAR; PG8_SCHED;
.LBB0_1007:
	s_add_u32 s24, s22, 0x100
	s_addc_u32 s25, s23, 0
	s_add_i32 s49, 0, 0x10000
	s_cmpk_eq_i32 s48, 0x54
	s_cselect_b32 s29, s1, s25
	s_cselect_b32 s28, s0, s24
	s_cselect_b32 s27, s21, s47
	s_cselect_b32 s26, s20, s46
	s_add_i32 s50, 0, 0x14000
	v_add_u32_e32 v126, s49, v247
	v_add_u32_e32 v158, s50, v247
	ds_read_b128 v[90:93], v126
	ds_read_b128 v[102:105], v126 offset:1024
	ds_read_b128 v[114:117], v126 offset:2048
	ds_read_b128 v[126:129], v126 offset:3072
	ds_read_b128 v[138:141], v158
	ds_read_b128 v[142:145], v158 offset:1024
	ds_read_b128 v[154:157], v158 offset:2048
	ds_read_b128 v[158:161], v158 offset:3072
	v_lshl_add_u64 v[204:205], s[22:23], 0, v[200:201]
	s_add_i32 m0, s8, 0xc000
	ds_read_b128 v[162:165], v249
	ds_read_b128 v[166:169], v249 offset:1024
	ds_read_b128 v[170:173], v249 offset:2048
	ds_read_b128 v[174:177], v249 offset:3072
	ds_read_b128 v[178:181], v249 offset:4096
	ds_read_b128 v[182:185], v249 offset:5120
	ds_read_b128 v[186:189], v249 offset:6144
	ds_read_b128 v[190:193], v249 offset:7168
	global_load_lds_dwordx4 v[204:205], off
	v_lshl_add_u64 v[204:205], s[22:23], 0, v[202:203]
	s_add_i32 m0, s8, 0xe000
	s_nop 0
	global_load_lds_dwordx4 v[204:205], off
	s_waitcnt vmcnt(8)
	s_waitcnt lgkmcnt(0)
	s_barrier
	s_setprio 1
	s_waitcnt lgkmcnt(0)
	v_mfma_f32_16x16x32_bf16 v[150:153], v[90:93], v[162:165], v[150:153]
	v_mfma_f32_16x16x32_bf16 v[150:153], v[102:105], v[166:169], v[150:153]
	v_mfma_f32_16x16x32_bf16 v[146:149], v[114:117], v[162:165], v[146:149]
	v_mfma_f32_16x16x32_bf16 v[146:149], v[126:129], v[166:169], v[146:149]
	v_mfma_f32_16x16x32_bf16 v[118:121], v[114:117], v[170:173], v[118:121]
	v_mfma_f32_16x16x32_bf16 v[118:121], v[126:129], v[174:177], v[118:121]
	v_mfma_f32_16x16x32_bf16 v[122:125], v[90:93], v[170:173], v[122:125]
	v_mfma_f32_16x16x32_bf16 v[122:125], v[102:105], v[174:177], v[122:125]
	v_mfma_f32_16x16x32_bf16 v[98:101], v[90:93], v[178:181], v[98:101]
	v_mfma_f32_16x16x32_bf16 v[98:101], v[102:105], v[182:185], v[98:101]
	v_mfma_f32_16x16x32_bf16 v[94:97], v[114:117], v[178:181], v[94:97]
	v_mfma_f32_16x16x32_bf16 v[94:97], v[126:129], v[182:185], v[94:97]
	v_mfma_f32_16x16x32_bf16 v[74:77], v[114:117], v[186:189], v[74:77]
	v_mfma_f32_16x16x32_bf16 v[74:77], v[126:129], v[190:193], v[74:77]
	v_mfma_f32_16x16x32_bf16 v[78:81], v[90:93], v[186:189], v[78:81]
	v_mfma_f32_16x16x32_bf16 v[78:81], v[102:105], v[190:193], v[78:81]
	s_setprio 0
	s_setprio 1
	v_mfma_f32_16x16x32_bf16 v[134:137], v[138:141], v[162:165], v[134:137]
	v_mfma_f32_16x16x32_bf16 v[134:137], v[142:145], v[166:169], v[134:137]
	v_mfma_f32_16x16x32_bf16 v[130:133], v[154:157], v[162:165], v[130:133]
	v_mfma_f32_16x16x32_bf16 v[130:133], v[158:161], v[166:169], v[130:133]
	v_mfma_f32_16x16x32_bf16 v[106:109], v[154:157], v[170:173], v[106:109]
	v_mfma_f32_16x16x32_bf16 v[106:109], v[158:161], v[174:177], v[106:109]
	v_mfma_f32_16x16x32_bf16 v[110:113], v[138:141], v[170:173], v[110:113]
	v_mfma_f32_16x16x32_bf16 v[110:113], v[142:145], v[174:177], v[110:113]
	v_mfma_f32_16x16x32_bf16 v[86:89], v[138:141], v[178:181], v[86:89]
	v_mfma_f32_16x16x32_bf16 v[86:89], v[142:145], v[182:185], v[86:89]
	v_mfma_f32_16x16x32_bf16 v[82:85], v[154:157], v[178:181], v[82:85]
	v_mfma_f32_16x16x32_bf16 v[82:85], v[158:161], v[182:185], v[82:85]
	v_mfma_f32_16x16x32_bf16 v[66:69], v[154:157], v[186:189], v[66:69]
	v_mfma_f32_16x16x32_bf16 v[66:69], v[158:161], v[190:193], v[66:69]
	v_mfma_f32_16x16x32_bf16 v[70:73], v[138:141], v[186:189], v[70:73]
	v_mfma_f32_16x16x32_bf16 v[70:73], v[142:145], v[190:193], v[70:73]
	s_setprio 0
	s_barrier
	s_add_i32 s22, s49, s7
	v_lshl_add_u64 v[204:205], s[26:27], 0, v[0:1]
	s_mov_b32 m0, s22
	ds_read_b128 v[162:165], v249 offset:16384
	ds_read_b128 v[166:169], v249 offset:17408
	ds_read_b128 v[170:173], v249 offset:18432
	ds_read_b128 v[174:177], v249 offset:19456
	ds_read_b128 v[178:181], v249 offset:20480
	ds_read_b128 v[182:185], v249 offset:21504
	ds_read_b128 v[186:189], v249 offset:22528
	ds_read_b128 v[190:193], v249 offset:23552
	global_load_lds_dwordx4 v[204:205], off
	s_add_i32 m0, s22, 0x2000
	s_add_u32 s22, s26, 0x160000
	v_lshl_add_u64 v[206:207], s[26:27], 0, v[194:195]
	s_addc_u32 s23, s27, 0
	s_add_i32 s49, s50, s7
	global_load_lds_dwordx4 v[206:207], off
	v_lshl_add_u64 v[208:209], s[22:23], 0, v[0:1]
	s_mov_b32 m0, s49
	v_lshl_add_u64 v[210:211], s[28:29], 0, v[196:197]
	global_load_lds_dwordx4 v[208:209], off
	v_lshl_add_u64 v[208:209], s[22:23], 0, v[194:195]
	s_add_i32 m0, s49, 0x2000
	s_nop 0
	global_load_lds_dwordx4 v[208:209], off
	v_lshl_add_u64 v[208:209], s[28:29], 0, v[198:199]
	s_mov_b32 m0, s8
	s_nop 0
	global_load_lds_dwordx4 v[208:209], off
	s_mov_b32 m0, s9
	s_nop 0
	global_load_lds_dwordx4 v[210:211], off
	s_waitcnt vmcnt(8)
	s_waitcnt lgkmcnt(0)
	s_barrier
; #define PG8_STAGE(bufoff, gbase, voff) do { _Pragma("unroll") for (int _i = 0; _i < 2; ++_i) \
;         __builtin_amdgcn_global_load_lds((const unsigned*)((const char*)(gbase) + (voff)[_i]), (LAS unsigned*)(lds + (bufoff) + ldsw + _i * 8192), 16, 0, 0); } while (0)
; #define PG8_LDA(dst, b, h) do { _Pragma("unroll") for (int m = 0; m < 4; ++m) _Pragma("unroll") for (int k = 0; k < 2; ++k) dst[m][k] = *(const LAS bf16x8*)(lds + PG8_SA(b, h) + aoff + m * 2048 + k * 1024); } while (0)
; #define PG8_LDB(dst, b, h) do { _Pragma("unroll") for (int n = 0; n < 2; ++n) _Pragma("unroll") for (int k = 0; k < 2; ++k) dst[n][k] = *(const LAS bf16x8*)(lds + PG8_SB(b, h) + boff + n * 2048 + k * 1024); } while (0)
; #define PG8_MMA(ai, bj, At, Bt) do { __builtin_amdgcn_s_setprio(1); _Pragma("unroll") for (int m = 0; m < 4; ++m) _Pragma("unroll") for (int n = 0; n < 2; ++n) _Pragma("unroll") for (int k = 0; k < 2; ++k) \
;         acc[ai][bj][m][n] = __builtin_amdgcn_mfma_f32_16x16x32_bf16(Bt[n][k], At[m][k], acc[ai][bj][m][n], 0, 0, 0); __builtin_amdgcn_s_setprio(0); } while (0)
; #define PG8_WAIT_V(n) asm volatile("s_waitcnt vmcnt(" #n ")" ::: "memory")
; #define PG8_WAIT_L(n) asm volatile("s_waitcnt lgkmcnt(" #n ")" ::: "memory")
; #define PG8_BAR __builtin_amdgcn_s_barrier()
; #define PG8_SCHED __builtin_amdgcn_sched_barrier(0)
; template <class Epi, class Sched, bool ALIGN_EPI = false, bool SP2 = false>
; __device__ __forceinline__ void gemm_phase(LAS unsigned char* lds, const Gemm g, const Sched& S, const Epi& E) {
;     ...
;             PG8_WAIT_V(8); PG8_WAIT_L(0); PG8_BAR; PG8_MMA(1, 0, At, B0); PG8_MMA(1, 1, At, B1); PG8_BAR; PG8_SCHED;
;             PG8_LDB(B0, 1, 0); PG8_LDB(B1, 1, 1); PG8_SCHED; PG8_LDA(At, 1, 0); PG8_STAGE(PG8_SA(0, 1), a2 + hstep, voffA);
;             PG8_WAIT_V(8); PG8_WAIT_L(0); PG8_BAR; PG8_MMA(0, 0, At, B0); PG8_MMA(0, 1, At, B1); PG8_BAR; PG8_SCHED;
	s_setprio 1
	s_waitcnt lgkmcnt(0)
	v_mfma_f32_16x16x32_bf16 v[62:65], v[90:93], v[162:165], v[62:65]
	v_mfma_f32_16x16x32_bf16 v[62:65], v[102:105], v[166:169], v[62:65]
	v_mfma_f32_16x16x32_bf16 v[58:61], v[114:117], v[162:165], v[58:61]
	v_mfma_f32_16x16x32_bf16 v[58:61], v[126:129], v[166:169], v[58:61]
	v_mfma_f32_16x16x32_bf16 v[42:45], v[114:117], v[170:173], v[42:45]
	v_mfma_f32_16x16x32_bf16 v[42:45], v[126:129], v[174:177], v[42:45]
	v_mfma_f32_16x16x32_bf16 v[46:49], v[90:93], v[170:173], v[46:49]
	v_mfma_f32_16x16x32_bf16 v[46:49], v[102:105], v[174:177], v[46:49]
	v_mfma_f32_16x16x32_bf16 v[30:33], v[90:93], v[178:181], v[30:33]
	v_mfma_f32_16x16x32_bf16 v[30:33], v[102:105], v[182:185], v[30:33]
	v_mfma_f32_16x16x32_bf16 v[26:29], v[114:117], v[178:181], v[26:29]
	v_mfma_f32_16x16x32_bf16 v[26:29], v[126:129], v[182:185], v[26:29]
	v_mfma_f32_16x16x32_bf16 v[10:13], v[114:117], v[186:189], v[10:13]
	v_mfma_f32_16x16x32_bf16 v[10:13], v[126:129], v[190:193], v[10:13]
	v_mfma_f32_16x16x32_bf16 v[14:17], v[90:93], v[186:189], v[14:17]
	v_mfma_f32_16x16x32_bf16 v[14:17], v[102:105], v[190:193], v[14:17]
	s_setprio 0
	s_setprio 1
	v_mfma_f32_16x16x32_bf16 v[54:57], v[138:141], v[162:165], v[54:57]
	v_mfma_f32_16x16x32_bf16 v[54:57], v[142:145], v[166:169], v[54:57]
	v_mfma_f32_16x16x32_bf16 v[50:53], v[154:157], v[162:165], v[50:53]
	v_mfma_f32_16x16x32_bf16 v[50:53], v[158:161], v[166:169], v[50:53]
	v_mfma_f32_16x16x32_bf16 v[34:37], v[154:157], v[170:173], v[34:37]
	v_mfma_f32_16x16x32_bf16 v[34:37], v[158:161], v[174:177], v[34:37]
	v_mfma_f32_16x16x32_bf16 v[38:41], v[138:141], v[170:173], v[38:41]
	v_mfma_f32_16x16x32_bf16 v[38:41], v[142:145], v[174:177], v[38:41]
	v_mfma_f32_16x16x32_bf16 v[22:25], v[138:141], v[178:181], v[22:25]
	v_mfma_f32_16x16x32_bf16 v[22:25], v[142:145], v[182:185], v[22:25]
	v_mfma_f32_16x16x32_bf16 v[18:21], v[154:157], v[178:181], v[18:21]
	v_mfma_f32_16x16x32_bf16 v[18:21], v[158:161], v[182:185], v[18:21]
	v_mfma_f32_16x16x32_bf16 v[2:5], v[154:157], v[186:189], v[2:5]
	v_mfma_f32_16x16x32_bf16 v[2:5], v[158:161], v[190:193], v[2:5]
	v_mfma_f32_16x16x32_bf16 v[6:9], v[138:141], v[186:189], v[6:9]
	v_mfma_f32_16x16x32_bf16 v[6:9], v[142:145], v[190:193], v[6:9]
	s_setprio 0
	s_barrier
	s_add_i32 s49, 0, 0x18000
	s_add_i32 s50, 0, 0x1c000
	v_add_u32_e32 v126, s49, v247
	v_add_u32_e32 v158, s50, v247
	ds_read_b128 v[90:93], v126
	ds_read_b128 v[102:105], v126 offset:1024
	ds_read_b128 v[114:117], v126 offset:2048
	ds_read_b128 v[126:129], v126 offset:3072
	ds_read_b128 v[138:141], v158
	ds_read_b128 v[142:145], v158 offset:1024
	ds_read_b128 v[154:157], v158 offset:2048
	ds_read_b128 v[158:161], v158 offset:3072
	s_add_u32 s22, s28, 0x160000
	s_addc_u32 s23, s29, 0
	s_mov_b32 m0, s30
	v_lshl_add_u64 v[212:213], s[22:23], 0, v[198:199]
	ds_read_b128 v[162:165], v249 offset:32768
	ds_read_b128 v[166:169], v249 offset:33792
	ds_read_b128 v[170:173], v249 offset:34816
	ds_read_b128 v[174:177], v249 offset:35840
	ds_read_b128 v[178:181], v249 offset:36864
	ds_read_b128 v[182:185], v249 offset:37888
	ds_read_b128 v[186:189], v249 offset:38912
	ds_read_b128 v[190:193], v249 offset:39936
	global_load_lds_dwordx4 v[212:213], off
	v_lshl_add_u64 v[212:213], s[22:23], 0, v[196:197]
	s_mov_b32 m0, s31
	s_nop 0
	global_load_lds_dwordx4 v[212:213], off
	s_waitcnt vmcnt(8)
	s_waitcnt lgkmcnt(0)
	s_barrier
	s_setprio 1
	s_waitcnt lgkmcnt(0)
	v_mfma_f32_16x16x32_bf16 v[150:153], v[90:93], v[162:165], v[150:153]
	v_mfma_f32_16x16x32_bf16 v[150:153], v[102:105], v[166:169], v[150:153]
	v_mfma_f32_16x16x32_bf16 v[146:149], v[114:117], v[162:165], v[146:149]
	v_mfma_f32_16x16x32_bf16 v[146:149], v[126:129], v[166:169], v[146:149]
	v_mfma_f32_16x16x32_bf16 v[118:121], v[114:117], v[170:173], v[118:121]
	v_mfma_f32_16x16x32_bf16 v[118:121], v[126:129], v[174:177], v[118:121]
	v_mfma_f32_16x16x32_bf16 v[122:125], v[90:93], v[170:173], v[122:125]
	v_mfma_f32_16x16x32_bf16 v[122:125], v[102:105], v[174:177], v[122:125]
	v_mfma_f32_16x16x32_bf16 v[98:101], v[90:93], v[178:181], v[98:101]
	v_mfma_f32_16x16x32_bf16 v[98:101], v[102:105], v[182:185], v[98:101]
	v_mfma_f32_16x16x32_bf16 v[94:97], v[114:117], v[178:181], v[94:97]
	v_mfma_f32_16x16x32_bf16 v[94:97], v[126:129], v[182:185], v[94:97]
	v_mfma_f32_16x16x32_bf16 v[74:77], v[114:117], v[186:189], v[74:77]
	v_mfma_f32_16x16x32_bf16 v[74:77], v[126:129], v[190:193], v[74:77]
	v_mfma_f32_16x16x32_bf16 v[78:81], v[90:93], v[186:189], v[78:81]
	v_mfma_f32_16x16x32_bf16 v[78:81], v[102:105], v[190:193], v[78:81]
	s_setprio 0
	s_setprio 1
	v_mfma_f32_16x16x32_bf16 v[134:137], v[138:141], v[162:165], v[134:137]
	v_mfma_f32_16x16x32_bf16 v[134:137], v[142:145], v[166:169], v[134:137]
	v_mfma_f32_16x16x32_bf16 v[130:133], v[154:157], v[162:165], v[130:133]
	v_mfma_f32_16x16x32_bf16 v[130:133], v[158:161], v[166:169], v[130:133]
	v_mfma_f32_16x16x32_bf16 v[106:109], v[154:157], v[170:173], v[106:109]
	v_mfma_f32_16x16x32_bf16 v[106:109], v[158:161], v[174:177], v[106:109]
	v_mfma_f32_16x16x32_bf16 v[110:113], v[138:141], v[170:173], v[110:113]
	v_mfma_f32_16x16x32_bf16 v[110:113], v[142:145], v[174:177], v[110:113]
	v_mfma_f32_16x16x32_bf16 v[86:89], v[138:141], v[178:181], v[86:89]
	v_mfma_f32_16x16x32_bf16 v[86:89], v[142:145], v[182:185], v[86:89]
	v_mfma_f32_16x16x32_bf16 v[82:85], v[154:157], v[178:181], v[82:85]
	v_mfma_f32_16x16x32_bf16 v[82:85], v[158:161], v[182:185], v[82:85]
	v_mfma_f32_16x16x32_bf16 v[66:69], v[154:157], v[186:189], v[66:69]
	v_mfma_f32_16x16x32_bf16 v[66:69], v[158:161], v[190:193], v[66:69]
	v_mfma_f32_16x16x32_bf16 v[70:73], v[138:141], v[186:189], v[70:73]
	v_mfma_f32_16x16x32_bf16 v[70:73], v[142:145], v[190:193], v[70:73]
	s_setprio 0
	s_barrier
; #define PG8_STAGE(bufoff, gbase, voff) do { _Pragma("unroll") for (int _i = 0; _i < 2; ++_i) \
;         __builtin_amdgcn_global_load_lds((const unsigned*)((const char*)(gbase) + (voff)[_i]), (LAS unsigned*)(lds + (bufoff) + ldsw + _i * 8192), 16, 0, 0); } while (0)
; #define PG8_LDA(dst, b, h) do { _Pragma("unroll") for (int m = 0; m < 4; ++m) _Pragma("unroll") for (int k = 0; k < 2; ++k) dst[m][k] = *(const LAS bf16x8*)(lds + PG8_SA(b, h) + aoff + m * 2048 + k * 1024); } while (0)
; #define PG8_MMA(ai, bj, At, Bt) do { __builtin_amdgcn_s_setprio(1); _Pragma("unroll") for (int m = 0; m < 4; ++m) _Pragma("unroll") for (int n = 0; n < 2; ++n) _Pragma("unroll") for (int k = 0; k < 2; ++k) \
;         acc[ai][bj][m][n] = __builtin_amdgcn_mfma_f32_16x16x32_bf16(Bt[n][k], At[m][k], acc[ai][bj][m][n], 0, 0, 0); __builtin_amdgcn_s_setprio(0); } while (0)
; #define PG8_WAIT_V(n) asm volatile("s_waitcnt vmcnt(" #n ")" ::: "memory")
; #define PG8_WAIT_L(n) asm volatile("s_waitcnt lgkmcnt(" #n ")" ::: "memory")
; #define PG8_BAR __builtin_amdgcn_s_barrier()
; #define PG8_SCHED __builtin_amdgcn_sched_barrier(0)
; template <class Epi, class Sched, bool ALIGN_EPI = false, bool SP2 = false>
; __device__ __forceinline__ void gemm_phase(LAS unsigned char* lds, const Gemm g, const Sched& S, const Epi& E) {
;     ...
;             PG8_LDA(At, 1, 1); PG8_STAGE(PG8_SB(1, 0), b3, voffB); PG8_STAGE(PG8_SB(1, 1), b3 + hstep, voffB); PG8_STAGE(PG8_SA(1, 0), a3, voffA);
;             PG8_WAIT_V(8); PG8_WAIT_L(0); PG8_BAR; PG8_MMA(1, 0, At, B0); PG8_MMA(1, 1, At, B1); PG8_BAR; PG8_SCHED;
	s_add_i32 s22, s49, s7
	v_lshl_add_u64 v[204:205], v[204:205], 0, s[12:13]
	s_mov_b32 m0, s22
	ds_read_b128 v[162:165], v249 offset:49152
	ds_read_b128 v[166:169], v249 offset:50176
	ds_read_b128 v[170:173], v249 offset:51200
	ds_read_b128 v[174:177], v249 offset:52224
	ds_read_b128 v[178:181], v249 offset:53248
	ds_read_b128 v[182:185], v249 offset:54272
	ds_read_b128 v[186:189], v249 offset:55296
	ds_read_b128 v[190:193], v249 offset:56320
	global_load_lds_dwordx4 v[204:205], off
	s_add_i32 m0, s22, 0x2000
	s_add_u32 s22, s26, 0x160080
	v_lshl_add_u64 v[204:205], v[206:207], 0, s[12:13]
	s_addc_u32 s23, s27, 0
	s_add_i32 s26, s50, s7
	global_load_lds_dwordx4 v[204:205], off
	v_lshl_add_u64 v[204:205], s[22:23], 0, v[0:1]
	s_mov_b32 m0, s26
	s_nop 0
	global_load_lds_dwordx4 v[204:205], off
	v_lshl_add_u64 v[204:205], s[22:23], 0, v[194:195]
	s_add_i32 m0, s26, 0x2000
	s_nop 0
	global_load_lds_dwordx4 v[204:205], off
	v_lshl_add_u64 v[204:205], v[208:209], 0, s[12:13]
	s_mov_b32 m0, s35
	s_nop 0
	global_load_lds_dwordx4 v[204:205], off
	v_lshl_add_u64 v[204:205], v[210:211], 0, s[12:13]
	s_mov_b32 m0, s40
	s_nop 0
	global_load_lds_dwordx4 v[204:205], off
	s_waitcnt vmcnt(8)
	s_waitcnt lgkmcnt(0)
	s_barrier
	s_setprio 1
	s_waitcnt lgkmcnt(0)
	v_mfma_f32_16x16x32_bf16 v[62:65], v[90:93], v[162:165], v[62:65]
	v_mfma_f32_16x16x32_bf16 v[62:65], v[102:105], v[166:169], v[62:65]
	v_mfma_f32_16x16x32_bf16 v[58:61], v[114:117], v[162:165], v[58:61]
	v_mfma_f32_16x16x32_bf16 v[58:61], v[126:129], v[166:169], v[58:61]
	v_mfma_f32_16x16x32_bf16 v[42:45], v[114:117], v[170:173], v[42:45]
	v_mfma_f32_16x16x32_bf16 v[42:45], v[126:129], v[174:177], v[42:45]
	v_mfma_f32_16x16x32_bf16 v[46:49], v[90:93], v[170:173], v[46:49]
	v_mfma_f32_16x16x32_bf16 v[46:49], v[102:105], v[174:177], v[46:49]
	v_mfma_f32_16x16x32_bf16 v[30:33], v[90:93], v[178:181], v[30:33]
	v_mfma_f32_16x16x32_bf16 v[30:33], v[102:105], v[182:185], v[30:33]
	v_mfma_f32_16x16x32_bf16 v[26:29], v[114:117], v[178:181], v[26:29]
	v_mfma_f32_16x16x32_bf16 v[26:29], v[126:129], v[182:185], v[26:29]
	v_mfma_f32_16x16x32_bf16 v[10:13], v[114:117], v[186:189], v[10:13]
	v_mfma_f32_16x16x32_bf16 v[10:13], v[126:129], v[190:193], v[10:13]
	v_mfma_f32_16x16x32_bf16 v[14:17], v[90:93], v[186:189], v[14:17]
	v_mfma_f32_16x16x32_bf16 v[14:17], v[102:105], v[190:193], v[14:17]
	s_setprio 0
	s_setprio 1
	v_mfma_f32_16x16x32_bf16 v[54:57], v[138:141], v[162:165], v[54:57]
	v_mfma_f32_16x16x32_bf16 v[54:57], v[142:145], v[166:169], v[54:57]
	v_mfma_f32_16x16x32_bf16 v[50:53], v[154:157], v[162:165], v[50:53]
	v_mfma_f32_16x16x32_bf16 v[50:53], v[158:161], v[166:169], v[50:53]
	v_mfma_f32_16x16x32_bf16 v[34:37], v[154:157], v[170:173], v[34:37]
	v_mfma_f32_16x16x32_bf16 v[34:37], v[158:161], v[174:177], v[34:37]
	v_mfma_f32_16x16x32_bf16 v[38:41], v[138:141], v[170:173], v[38:41]
	v_mfma_f32_16x16x32_bf16 v[38:41], v[142:145], v[174:177], v[38:41]
	v_mfma_f32_16x16x32_bf16 v[22:25], v[138:141], v[178:181], v[22:25]
	v_mfma_f32_16x16x32_bf16 v[22:25], v[142:145], v[182:185], v[22:25]
	v_mfma_f32_16x16x32_bf16 v[18:21], v[154:157], v[178:181], v[18:21]
	v_mfma_f32_16x16x32_bf16 v[18:21], v[158:161], v[182:185], v[18:21]
	v_mfma_f32_16x16x32_bf16 v[2:5], v[154:157], v[186:189], v[2:5]
	v_mfma_f32_16x16x32_bf16 v[2:5], v[158:161], v[190:193], v[2:5]
	v_mfma_f32_16x16x32_bf16 v[6:9], v[138:141], v[186:189], v[6:9]
	v_mfma_f32_16x16x32_bf16 v[6:9], v[142:145], v[190:193], v[6:9]
	s_setprio 0
	s_barrier
	s_add_i32 s48, s48, 2
	s_add_u32 s46, s46, 0x100
	s_addc_u32 s47, s47, 0
	s_cmpk_gt_u32 s48, 0x55
	s_mov_b64 s[22:23], s[24:25]
	s_cbranch_scc0 .LBB0_1007
	s_and_b64 vcc, exec, s[18:19]
	s_cbranch_vccz .LBB0_1010
	s_barrier
